# P6 fused-final-norm epilogue: residual / row-scale / norm-weight loads issued up front
# speedup vs baseline: 1.0596x; 1.0083x over previous
;     __device__ __forceinline__ void operator()(f32x4 (&acc)[2][2][4][2], const pg8::Unit& u, int wr, int wc, int fr, int fq) const {
;         const int row0 = u.pm * 256 + wr * 64 + fr, col0 = u.pn * 256 + wc * 32 + 8 * fq;
; #pragma unroll
;         for (int ai = 0; ai < 2; ++ai)
; #pragma unroll
;             for (int m = 0; m < 4; ++m) {
;                 const int row = row0 + ai * 128 + m * 16;
;                 float ss = 0.f;
; #pragma unroll
;                 for (int bj = 0; bj < 2; ++bj) {
;                     const int c = col0 + bj * 128;
;                     const h16x8 r8 = *(const h16x8*)(res16 + (size_t)row * D + c);
;                     f32x4 v0 = acc[ai][bj][m][0], v1 = acc[ai][bj][m][1];
; #pragma unroll
;                     for (int j = 0; j < 4; ++j) { v0[j] += (float)r8[j]; v1[j] += (float)r8[4 + j]; }
;                     acc[ai][bj][m][0] = v0; acc[ai][bj][m][1] = v1;
;                     ss += v0[0] * v0[0] + v0[1] * v0[1] + v0[2] * v0[2] + v0[3] * v0[3] + v1[0] * v1[0] + v1[1] * v1[1] + v1[2] * v1[2] + v1[3] * v1[3];
;                 }
;                 ss += __shfl_xor(ss, 16); ss += __shfl_xor(ss, 32);
;                 if (fq == 0) atomicAdd(rowss + row, ss);
.LBB0_575:
	s_lshl_b32 s1, s0, 8
	v_lshlrev_b32_e32 v139, 3, v137
	s_add_i32 s1, s1, s43
	v_or_b32_e32 v138, s1, v147
	v_lshl_or_b32 v139, s47, 8, v139
	v_or_b32_e32 v140, s44, v139
	v_ashrrev_i32_e32 v139, 31, v138
	v_lshlrev_b64 v[142:143], 11, v[138:139]
	v_lshl_add_u64 v[142:143], s[10:11], 0, v[142:143]
	v_ashrrev_i32_e32 v141, 31, v140
	v_lshl_add_u64 v[148:149], v[140:141], 1, v[142:143]
	s_barrier
	global_load_dwordx4 v[142:145], v[148:149], off
	s_nop 0
	global_load_dwordx4 v[148:151], v[148:149], off offset:256
	v_lshlrev_b32_e32 v252, 11, v138
	v_lshl_add_u32 v252, v140, 1, v252
	v_add_u32_e32 v200, 0x8000, v252
	global_load_dwordx4 v[184:187], v200, s[10:11]
	global_load_dwordx4 v[188:191], v200, s[10:11] offset:256
	v_add_u32_e32 v201, 0x10000, v252
	global_load_dwordx4 v[192:195], v201, s[10:11]
	global_load_dwordx4 v[196:199], v201, s[10:11] offset:256
	v_add_u32_e32 v202, 0x18000, v252
	global_load_dwordx4 v[204:207], v202, s[10:11]
	global_load_dwordx4 v[208:211], v202, s[10:11] offset:256
	v_add_u32_e32 v220, 0x40000, v252
	global_load_dwordx4 v[212:215], v220, s[10:11]
	global_load_dwordx4 v[216:219], v220, s[10:11] offset:256
	v_add_u32_e32 v221, 0x48000, v252
	global_load_dwordx4 v[228:231], v221, s[10:11]
	global_load_dwordx4 v[232:235], v221, s[10:11] offset:256
	v_add_u32_e32 v222, 0x50000, v252
	global_load_dwordx4 v[236:239], v222, s[10:11]
	global_load_dwordx4 v[240:243], v222, s[10:11] offset:256
	v_add_u32_e32 v223, 0x58000, v252
	global_load_dwordx4 v[244:247], v223, s[10:11]
	global_load_dwordx4 v[248:251], v223, s[10:11] offset:256
	v_xor_b32_e32 v147, 16, v129
	v_cmp_lt_i32_e32 vcc, v147, v135
	s_waitcnt vmcnt(0)
	v_cvt_f32_f16_e32 v152, v142
	v_cvt_f32_f16_sdwa v153, v142 dst_sel:DWORD dst_unused:UNUSED_PAD src0_sel:WORD_1
	v_cvt_f32_f16_e32 v154, v144
	v_cvt_f32_f16_sdwa v155, v144 dst_sel:DWORD dst_unused:UNUSED_PAD src0_sel:WORD_1
	v_cvt_f32_f16_e32 v158, v148
	v_cvt_f32_f16_sdwa v159, v148 dst_sel:DWORD dst_unused:UNUSED_PAD src0_sel:WORD_1
	v_cvt_f32_f16_e32 v156, v143
	v_cvt_f32_f16_sdwa v157, v143 dst_sel:DWORD dst_unused:UNUSED_PAD src0_sel:WORD_1
	v_cvt_f32_f16_e32 v160, v150
	v_cvt_f32_f16_sdwa v161, v150 dst_sel:DWORD dst_unused:UNUSED_PAD src0_sel:WORD_1
	v_cvt_f32_f16_e32 v148, v149
	v_cvt_f32_f16_sdwa v149, v149 dst_sel:DWORD dst_unused:UNUSED_PAD src0_sel:WORD_1
	v_cvt_f32_f16_e32 v144, v145
	v_cvt_f32_f16_sdwa v145, v145 dst_sel:DWORD dst_unused:UNUSED_PAD src0_sel:WORD_1
	v_pk_add_f32 v[142:143], v[124:125], v[152:153]
	v_pk_add_f32 v[124:125], v[120:121], v[154:155]
	v_pk_add_f32 v[120:121], v[116:117], v[158:159]
	v_cvt_f32_f16_e32 v150, v151
	v_cvt_f32_f16_sdwa v151, v151 dst_sel:DWORD dst_unused:UNUSED_PAD src0_sel:WORD_1
	v_pk_add_f32 v[126:127], v[126:127], v[156:157]
	v_pk_add_f32 v[116:117], v[112:113], v[160:161]
	v_pk_add_f32 v[118:119], v[118:119], v[148:149]
	v_pk_mul_f32 v[112:113], v[142:143], v[142:143]
	v_pk_mul_f32 v[152:153], v[120:121], v[120:121]
	v_pk_add_f32 v[122:123], v[122:123], v[144:145]
	v_pk_mul_f32 v[144:145], v[126:127], v[126:127]
	v_pk_mul_f32 v[154:155], v[118:119], v[118:119]
	v_add_f32_e32 v152, v152, v153
	v_add_f32_e32 v112, v112, v113
	v_add_f32_e32 v113, v154, v152
	v_add_f32_e32 v112, v144, v112
	v_pk_mul_f32 v[148:149], v[124:125], v[124:125]
	v_pk_mul_f32 v[156:157], v[116:117], v[116:117]
	v_add_f32_e32 v113, v155, v113
	v_add_f32_e32 v112, v145, v112
	v_pk_add_f32 v[114:115], v[114:115], v[150:151]
	v_add_f32_e32 v113, v156, v113
	v_add_f32_e32 v112, v148, v112
	v_pk_mul_f32 v[150:151], v[122:123], v[122:123]
	v_pk_mul_f32 v[158:159], v[114:115], v[114:115]
	v_add_f32_e32 v113, v157, v113
	v_add_f32_e32 v112, v149, v112
	v_add_f32_e32 v113, v158, v113
	v_add_f32_e32 v112, v150, v112
	v_cndmask_b32_e32 v147, v129, v147, vcc
	v_add_f32_e32 v113, v159, v113
	v_add_f32_e32 v112, v151, v112
	v_lshlrev_b32_e32 v147, 2, v147
	v_add_f32_e32 v112, v112, v113
	v_mov_b32_e32 v113, v112
	s_nop 1
	v_permlane16_swap_b32 v112, v113
	v_xor_b32_e32 v144, 32, v129
	v_cmp_lt_i32_e32 vcc, v144, v135
	s_nop 1
	v_cndmask_b32_e32 v144, v129, v144, vcc
	v_lshlrev_b32_e32 v166, 2, v144
	s_waitcnt lgkmcnt(0)
	v_add_f32_e32 v144, v112, v113
	v_mov_b32_e32 v145, v144
	s_nop 1
	v_permlane32_swap_b32 v144, v145
	v_cmp_eq_u32_e32 vcc, 0, v137
	v_lshl_add_u64 v[112:113], v[138:139], 2, s[14:15]
	s_and_saveexec_b64 s[4:5], vcc
	v_readlane_b32 s48, v253, 20
	v_readlane_b32 s60, v253, 32
	v_readlane_b32 s61, v253, 33
	v_readlane_b32 s62, v253, 34
	v_readlane_b32 s63, v253, 35
	v_readlane_b32 s49, v253, 21
	v_readlane_b32 s50, v253, 22
	v_readlane_b32 s51, v253, 23
	v_readlane_b32 s52, v253, 24
	v_readlane_b32 s53, v253, 25
	v_readlane_b32 s54, v253, 26
	v_readlane_b32 s55, v253, 27
	v_readlane_b32 s56, v253, 28
	v_readlane_b32 s57, v253, 29
	v_readlane_b32 s58, v253, 30
	v_readlane_b32 s59, v253, 31
	s_cbranch_execz .LBB0_577
	s_waitcnt lgkmcnt(0)
	v_add_f32_e32 v137, v144, v145
	global_atomic_add_f32 v[112:113], v137, off
;     __device__ __forceinline__ void operator()(f32x4 (&acc)[2][2][4][2], const pg8::Unit& u, int wr, int wc, int fr, int fq) const {
;     ...
;         for (int ai = 0; ai < 2; ++ai)
; #pragma unroll
;             for (int m = 0; m < 4; ++m) {
;                 const int row = row0 + ai * 128 + m * 16;
;                 float ss = 0.f;
; #pragma unroll
;                 for (int bj = 0; bj < 2; ++bj) {
;                     const int c = col0 + bj * 128;
;                     const h16x8 r8 = *(const h16x8*)(res16 + (size_t)row * D + c);
;                     f32x4 v0 = acc[ai][bj][m][0], v1 = acc[ai][bj][m][1];
; #pragma unroll
;                     for (int j = 0; j < 4; ++j) { v0[j] += (float)r8[j]; v1[j] += (float)r8[4 + j]; }
;                     acc[ai][bj][m][0] = v0; acc[ai][bj][m][1] = v1;
;                     ss += v0[0] * v0[0] + v0[1] * v0[1] + v0[2] * v0[2] + v0[3] * v0[3] + v1[0] * v1[0] + v1[1] * v1[1] + v1[2] * v1[2] + v1[3] * v1[3];
;                 }
;                 ss += __shfl_xor(ss, 16); ss += __shfl_xor(ss, 32);
;                 if (fq == 0) atomicAdd(rowss + row, ss);
.LBB0_577:
	s_or_b64 exec, exec, s[4:5]
	v_or_b32_e32 v144, 16, v138
	s_waitcnt lgkmcnt(0)
	v_ashrrev_i32_e32 v145, 31, v144
	v_lshlrev_b64 v[148:149], 11, v[144:145]
	v_lshl_add_u64 v[148:149], s[10:11], 0, v[148:149]
	v_lshl_add_u64 v[152:153], v[140:141], 1, v[148:149]
	v_mov_b32_e32 v148, v184
	v_mov_b32_e32 v149, v185
	v_mov_b32_e32 v150, v186
	v_mov_b32_e32 v151, v187
	s_nop 0
	v_mov_b32_e32 v152, v188
	v_mov_b32_e32 v153, v189
	v_mov_b32_e32 v154, v190
	v_mov_b32_e32 v155, v191
	s_nop 0
	v_cvt_f32_f16_e32 v156, v148
	v_cvt_f32_f16_sdwa v157, v148 dst_sel:DWORD dst_unused:UNUSED_PAD src0_sel:WORD_1
	s_nop 0
	v_cvt_f32_f16_e32 v162, v152
	v_cvt_f32_f16_sdwa v163, v152 dst_sel:DWORD dst_unused:UNUSED_PAD src0_sel:WORD_1
	v_cvt_f32_f16_e32 v158, v150
	v_cvt_f32_f16_sdwa v159, v150 dst_sel:DWORD dst_unused:UNUSED_PAD src0_sel:WORD_1
	v_cvt_f32_f16_e32 v160, v149
	v_cvt_f32_f16_sdwa v161, v149 dst_sel:DWORD dst_unused:UNUSED_PAD src0_sel:WORD_1
	v_cvt_f32_f16_e32 v152, v153
	v_cvt_f32_f16_sdwa v153, v153 dst_sel:DWORD dst_unused:UNUSED_PAD src0_sel:WORD_1
	v_cvt_f32_f16_e32 v150, v151
	v_cvt_f32_f16_sdwa v151, v151 dst_sel:DWORD dst_unused:UNUSED_PAD src0_sel:WORD_1
	v_cvt_f32_f16_e32 v164, v154
	v_cvt_f32_f16_sdwa v165, v154 dst_sel:DWORD dst_unused:UNUSED_PAD src0_sel:WORD_1
	v_pk_add_f32 v[148:149], v[108:109], v[156:157]
	v_pk_add_f32 v[100:101], v[100:101], v[162:163]
	v_cvt_f32_f16_e32 v154, v155
	v_cvt_f32_f16_sdwa v155, v155 dst_sel:DWORD dst_unused:UNUSED_PAD src0_sel:WORD_1
	v_pk_add_f32 v[108:109], v[104:105], v[158:159]
	v_pk_add_f32 v[110:111], v[110:111], v[160:161]
	v_pk_add_f32 v[102:103], v[102:103], v[152:153]
	v_pk_mul_f32 v[104:105], v[148:149], v[148:149]
	v_pk_mul_f32 v[156:157], v[100:101], v[100:101]
	v_pk_add_f32 v[106:107], v[106:107], v[150:151]
	v_pk_mul_f32 v[150:151], v[110:111], v[110:111]
	v_pk_mul_f32 v[158:159], v[102:103], v[102:103]
	v_add_f32_e32 v137, v156, v157
	v_add_f32_e32 v104, v104, v105
	v_pk_add_f32 v[96:97], v[96:97], v[164:165]
	v_add_f32_e32 v105, v158, v137
	v_add_f32_e32 v104, v150, v104
	v_pk_mul_f32 v[152:153], v[108:109], v[108:109]
	v_pk_mul_f32 v[160:161], v[96:97], v[96:97]
	v_add_f32_e32 v105, v159, v105
	v_add_f32_e32 v104, v151, v104
	v_pk_add_f32 v[98:99], v[98:99], v[154:155]
	v_add_f32_e32 v105, v160, v105
	v_add_f32_e32 v104, v152, v104
	v_pk_mul_f32 v[154:155], v[106:107], v[106:107]
	v_pk_mul_f32 v[162:163], v[98:99], v[98:99]
	v_add_f32_e32 v105, v161, v105
	v_add_f32_e32 v104, v153, v104
	v_add_f32_e32 v105, v162, v105
	v_add_f32_e32 v104, v154, v104
	v_add_f32_e32 v105, v163, v105
	v_add_f32_e32 v104, v155, v104
	v_add_f32_e32 v104, v104, v105
	v_mov_b32_e32 v105, v104
	s_nop 1
	v_permlane16_swap_b32 v104, v105
	v_lshl_add_u64 v[152:153], v[144:145], 2, s[14:15]
	s_waitcnt lgkmcnt(0)
	v_add_f32_e32 v104, v104, v105
	v_mov_b32_e32 v105, v104
	s_nop 1
	v_permlane32_swap_b32 v104, v105
	s_and_saveexec_b64 s[4:5], vcc
	s_cbranch_execz .LBB0_579
	s_waitcnt lgkmcnt(0)
	v_add_f32_e32 v104, v104, v105
	global_atomic_add_f32 v[152:153], v104, off
.LBB0_579:
	s_or_b64 exec, exec, s[4:5]
	v_or_b32_e32 v104, 32, v138
	s_waitcnt lgkmcnt(0)
	v_ashrrev_i32_e32 v105, 31, v104
	v_lshlrev_b64 v[150:151], 11, v[104:105]
	v_lshl_add_u64 v[150:151], s[10:11], 0, v[150:151]
	v_lshl_add_u64 v[150:151], v[140:141], 1, v[150:151]
	v_mov_b32_e32 v154, v192
	v_mov_b32_e32 v155, v193
	v_mov_b32_e32 v156, v194
	v_mov_b32_e32 v157, v195
	v_mov_b32_e32 v158, v196
	v_mov_b32_e32 v159, v197
	v_mov_b32_e32 v160, v198
	v_mov_b32_e32 v161, v199
	s_nop 0
	v_cvt_f32_f16_e32 v150, v154
	v_cvt_f32_f16_sdwa v151, v154 dst_sel:DWORD dst_unused:UNUSED_PAD src0_sel:WORD_1
	s_nop 0
	v_cvt_f32_f16_e32 v164, v158
	v_cvt_f32_f16_sdwa v165, v158 dst_sel:DWORD dst_unused:UNUSED_PAD src0_sel:WORD_1
	v_cvt_f32_f16_e32 v162, v156
	v_cvt_f32_f16_sdwa v163, v156 dst_sel:DWORD dst_unused:UNUSED_PAD src0_sel:WORD_1
	v_cvt_f32_f16_e32 v154, v155
	v_cvt_f32_f16_sdwa v155, v155 dst_sel:DWORD dst_unused:UNUSED_PAD src0_sel:WORD_1
	v_cvt_f32_f16_e32 v168, v160
	v_cvt_f32_f16_sdwa v169, v160 dst_sel:DWORD dst_unused:UNUSED_PAD src0_sel:WORD_1
	v_cvt_f32_f16_e32 v158, v159
	v_cvt_f32_f16_sdwa v159, v159 dst_sel:DWORD dst_unused:UNUSED_PAD src0_sel:WORD_1
	v_cvt_f32_f16_e32 v160, v161
	v_cvt_f32_f16_sdwa v161, v161 dst_sel:DWORD dst_unused:UNUSED_PAD src0_sel:WORD_1
	v_cvt_f32_f16_e32 v156, v157
	v_cvt_f32_f16_sdwa v157, v157 dst_sel:DWORD dst_unused:UNUSED_PAD src0_sel:WORD_1
	v_pk_add_f32 v[150:151], v[92:93], v[150:151]
	v_pk_add_f32 v[84:85], v[84:85], v[164:165]
	v_pk_add_f32 v[92:93], v[88:89], v[162:163]
	v_pk_add_f32 v[94:95], v[94:95], v[154:155]
	v_pk_add_f32 v[86:87], v[86:87], v[158:159]
	v_pk_add_f32 v[82:83], v[82:83], v[160:161]
	v_pk_mul_f32 v[88:89], v[150:151], v[150:151]
	v_pk_mul_f32 v[160:161], v[84:85], v[84:85]
	v_pk_mul_f32 v[154:155], v[94:95], v[94:95]
	v_pk_mul_f32 v[162:163], v[86:87], v[86:87]
	v_add_f32_e32 v137, v160, v161
	v_add_f32_e32 v88, v88, v89
	v_pk_add_f32 v[80:81], v[80:81], v[168:169]
	v_add_f32_e32 v89, v162, v137
	v_add_f32_e32 v88, v154, v88
	v_pk_add_f32 v[90:91], v[90:91], v[156:157]
	v_pk_mul_f32 v[156:157], v[92:93], v[92:93]
	v_pk_mul_f32 v[164:165], v[80:81], v[80:81]
	v_add_f32_e32 v89, v163, v89
	v_add_f32_e32 v88, v155, v88
	v_add_f32_e32 v89, v164, v89
	v_add_f32_e32 v88, v156, v88
	v_pk_mul_f32 v[158:159], v[90:91], v[90:91]
	v_pk_mul_f32 v[168:169], v[82:83], v[82:83]
	v_add_f32_e32 v89, v165, v89
	v_add_f32_e32 v88, v157, v88
	v_add_f32_e32 v89, v168, v89
	v_add_f32_e32 v88, v158, v88
	v_add_f32_e32 v89, v169, v89
	v_add_f32_e32 v88, v159, v88
	v_add_f32_e32 v88, v88, v89
	v_mov_b32_e32 v89, v88
	s_nop 1
	v_permlane16_swap_b32 v88, v89
	v_lshl_add_u64 v[156:157], v[104:105], 2, s[14:15]
	s_waitcnt lgkmcnt(0)
	v_add_f32_e32 v88, v88, v89
	v_mov_b32_e32 v89, v88
	s_nop 1
	v_permlane32_swap_b32 v88, v89
	s_and_saveexec_b64 s[4:5], vcc
	s_cbranch_execz .LBB0_581
	s_waitcnt lgkmcnt(0)
	v_add_f32_e32 v88, v88, v89
	global_atomic_add_f32 v[156:157], v88, off
;     __device__ __forceinline__ void operator()(f32x4 (&acc)[2][2][4][2], const pg8::Unit& u, int wr, int wc, int fr, int fq) const {
;     ...
;         for (int ai = 0; ai < 2; ++ai)
; #pragma unroll
;             for (int m = 0; m < 4; ++m) {
;                 const int row = row0 + ai * 128 + m * 16;
;                 float ss = 0.f;
; #pragma unroll
;                 for (int bj = 0; bj < 2; ++bj) {
;                     const int c = col0 + bj * 128;
;                     const h16x8 r8 = *(const h16x8*)(res16 + (size_t)row * D + c);
;                     f32x4 v0 = acc[ai][bj][m][0], v1 = acc[ai][bj][m][1];
; #pragma unroll
;                     for (int j = 0; j < 4; ++j) { v0[j] += (float)r8[j]; v1[j] += (float)r8[4 + j]; }
;                     acc[ai][bj][m][0] = v0; acc[ai][bj][m][1] = v1;
;                     ss += v0[0] * v0[0] + v0[1] * v0[1] + v0[2] * v0[2] + v0[3] * v0[3] + v1[0] * v1[0] + v1[1] * v1[1] + v1[2] * v1[2] + v1[3] * v1[3];
;                 }
;                 ss += __shfl_xor(ss, 16); ss += __shfl_xor(ss, 32);
;                 if (fq == 0) atomicAdd(rowss + row, ss);
.LBB0_581:
	s_or_b64 exec, exec, s[4:5]
	v_or_b32_e32 v88, 48, v138
	s_waitcnt lgkmcnt(0)
	v_ashrrev_i32_e32 v89, 31, v88
	v_lshlrev_b64 v[154:155], 11, v[88:89]
	v_lshl_add_u64 v[154:155], s[10:11], 0, v[154:155]
	v_lshl_add_u64 v[154:155], v[140:141], 1, v[154:155]
	v_mov_b32_e32 v158, v204
	v_mov_b32_e32 v159, v205
	v_mov_b32_e32 v160, v206
	v_mov_b32_e32 v161, v207
	v_mov_b32_e32 v162, v208
	v_mov_b32_e32 v163, v209
	v_mov_b32_e32 v164, v210
	v_mov_b32_e32 v165, v211
	s_nop 0
	v_cvt_f32_f16_e32 v154, v158
	v_cvt_f32_f16_sdwa v155, v158 dst_sel:DWORD dst_unused:UNUSED_PAD src0_sel:WORD_1
	s_nop 0
	v_cvt_f32_f16_e32 v170, v162
	v_cvt_f32_f16_sdwa v171, v162 dst_sel:DWORD dst_unused:UNUSED_PAD src0_sel:WORD_1
	v_cvt_f32_f16_e32 v168, v160
	v_cvt_f32_f16_sdwa v169, v160 dst_sel:DWORD dst_unused:UNUSED_PAD src0_sel:WORD_1
	v_cvt_f32_f16_e32 v158, v159
	v_cvt_f32_f16_sdwa v159, v159 dst_sel:DWORD dst_unused:UNUSED_PAD src0_sel:WORD_1
	v_cvt_f32_f16_e32 v172, v164
	v_cvt_f32_f16_sdwa v173, v164 dst_sel:DWORD dst_unused:UNUSED_PAD src0_sel:WORD_1
	v_cvt_f32_f16_e32 v162, v163
	v_cvt_f32_f16_sdwa v163, v163 dst_sel:DWORD dst_unused:UNUSED_PAD src0_sel:WORD_1
	v_cvt_f32_f16_e32 v164, v165
	v_cvt_f32_f16_sdwa v165, v165 dst_sel:DWORD dst_unused:UNUSED_PAD src0_sel:WORD_1
	v_cvt_f32_f16_e32 v160, v161
	v_cvt_f32_f16_sdwa v161, v161 dst_sel:DWORD dst_unused:UNUSED_PAD src0_sel:WORD_1
	v_pk_add_f32 v[154:155], v[76:77], v[154:155]
	v_pk_add_f32 v[68:69], v[68:69], v[170:171]
	v_pk_add_f32 v[76:77], v[72:73], v[168:169]
	v_pk_add_f32 v[78:79], v[78:79], v[158:159]
	v_pk_add_f32 v[70:71], v[70:71], v[162:163]
	v_pk_add_f32 v[66:67], v[66:67], v[164:165]
	v_pk_mul_f32 v[72:73], v[154:155], v[154:155]
	v_pk_mul_f32 v[164:165], v[68:69], v[68:69]
	v_pk_mul_f32 v[158:159], v[78:79], v[78:79]
	v_pk_mul_f32 v[168:169], v[70:71], v[70:71]
	v_add_f32_e32 v137, v164, v165
	v_add_f32_e32 v72, v72, v73
	v_pk_add_f32 v[64:65], v[64:65], v[172:173]
	v_add_f32_e32 v73, v168, v137
	v_add_f32_e32 v72, v158, v72
	v_pk_add_f32 v[74:75], v[74:75], v[160:161]
	v_pk_mul_f32 v[160:161], v[76:77], v[76:77]
	v_pk_mul_f32 v[170:171], v[64:65], v[64:65]
	v_add_f32_e32 v73, v169, v73
	v_add_f32_e32 v72, v159, v72
	v_add_f32_e32 v73, v170, v73
	v_add_f32_e32 v72, v160, v72
	v_pk_mul_f32 v[162:163], v[74:75], v[74:75]
	v_pk_mul_f32 v[172:173], v[66:67], v[66:67]
	v_add_f32_e32 v73, v171, v73
	v_add_f32_e32 v72, v161, v72
	v_add_f32_e32 v73, v172, v73
	v_add_f32_e32 v72, v162, v72
	v_add_f32_e32 v73, v173, v73
	v_add_f32_e32 v72, v163, v72
	v_add_f32_e32 v72, v72, v73
	v_mov_b32_e32 v73, v72
	s_nop 1
	v_permlane16_swap_b32 v72, v73
	v_lshl_add_u64 v[160:161], v[88:89], 2, s[14:15]
	s_waitcnt lgkmcnt(0)
	v_add_f32_e32 v72, v72, v73
	v_mov_b32_e32 v73, v72
	s_nop 1
	v_permlane32_swap_b32 v72, v73
	s_and_saveexec_b64 s[4:5], vcc
	s_cbranch_execz .LBB0_583
	s_waitcnt lgkmcnt(0)
	v_add_f32_e32 v72, v72, v73
	global_atomic_add_f32 v[160:161], v72, off
.LBB0_583:
	s_or_b64 exec, exec, s[4:5]
	v_add_u32_e32 v72, 0x80, v138
	s_waitcnt lgkmcnt(0)
	v_ashrrev_i32_e32 v73, 31, v72
	v_lshlrev_b64 v[158:159], 11, v[72:73]
	v_lshl_add_u64 v[158:159], s[10:11], 0, v[158:159]
	v_lshl_add_u64 v[158:159], v[140:141], 1, v[158:159]
	v_mov_b32_e32 v162, v212
	v_mov_b32_e32 v163, v213
	v_mov_b32_e32 v164, v214
	v_mov_b32_e32 v165, v215
	v_mov_b32_e32 v168, v216
	v_mov_b32_e32 v169, v217
	v_mov_b32_e32 v170, v218
	v_mov_b32_e32 v171, v219
	s_nop 0
	v_cvt_f32_f16_e32 v158, v162
	v_cvt_f32_f16_sdwa v159, v162 dst_sel:DWORD dst_unused:UNUSED_PAD src0_sel:WORD_1
	s_nop 0
	v_cvt_f32_f16_e32 v174, v168
	v_cvt_f32_f16_sdwa v175, v168 dst_sel:DWORD dst_unused:UNUSED_PAD src0_sel:WORD_1
	v_cvt_f32_f16_e32 v172, v164
	v_cvt_f32_f16_sdwa v173, v164 dst_sel:DWORD dst_unused:UNUSED_PAD src0_sel:WORD_1
	v_cvt_f32_f16_e32 v162, v163
	v_cvt_f32_f16_sdwa v163, v163 dst_sel:DWORD dst_unused:UNUSED_PAD src0_sel:WORD_1
	v_cvt_f32_f16_e32 v176, v170
	v_cvt_f32_f16_sdwa v177, v170 dst_sel:DWORD dst_unused:UNUSED_PAD src0_sel:WORD_1
	v_cvt_f32_f16_e32 v168, v169
	v_cvt_f32_f16_sdwa v169, v169 dst_sel:DWORD dst_unused:UNUSED_PAD src0_sel:WORD_1
	v_cvt_f32_f16_e32 v170, v171
	v_cvt_f32_f16_sdwa v171, v171 dst_sel:DWORD dst_unused:UNUSED_PAD src0_sel:WORD_1
	v_cvt_f32_f16_e32 v164, v165
	v_cvt_f32_f16_sdwa v165, v165 dst_sel:DWORD dst_unused:UNUSED_PAD src0_sel:WORD_1
	v_pk_add_f32 v[158:159], v[60:61], v[158:159]
	v_pk_add_f32 v[52:53], v[52:53], v[174:175]
	v_pk_add_f32 v[60:61], v[56:57], v[172:173]
	v_pk_add_f32 v[62:63], v[62:63], v[162:163]
	v_pk_add_f32 v[54:55], v[54:55], v[168:169]
	v_pk_add_f32 v[50:51], v[50:51], v[170:171]
	v_pk_mul_f32 v[56:57], v[158:159], v[158:159]
	v_pk_mul_f32 v[170:171], v[52:53], v[52:53]
	v_pk_mul_f32 v[162:163], v[62:63], v[62:63]
	v_pk_mul_f32 v[172:173], v[54:55], v[54:55]
	v_add_f32_e32 v137, v170, v171
	v_add_f32_e32 v56, v56, v57
	v_pk_add_f32 v[48:49], v[48:49], v[176:177]
	v_add_f32_e32 v57, v172, v137
	v_add_f32_e32 v56, v162, v56
	v_pk_add_f32 v[58:59], v[58:59], v[164:165]
	v_pk_mul_f32 v[164:165], v[60:61], v[60:61]
	v_pk_mul_f32 v[174:175], v[48:49], v[48:49]
	v_add_f32_e32 v57, v173, v57
	v_add_f32_e32 v56, v163, v56
	v_add_f32_e32 v57, v174, v57
	v_add_f32_e32 v56, v164, v56
	v_pk_mul_f32 v[168:169], v[58:59], v[58:59]
	v_pk_mul_f32 v[176:177], v[50:51], v[50:51]
	v_add_f32_e32 v57, v175, v57
	v_add_f32_e32 v56, v165, v56
	v_add_f32_e32 v57, v176, v57
	v_add_f32_e32 v56, v168, v56
	v_add_f32_e32 v57, v177, v57
	v_add_f32_e32 v56, v169, v56
	v_add_f32_e32 v56, v56, v57
	v_mov_b32_e32 v57, v56
	s_nop 1
	v_permlane16_swap_b32 v56, v57
	s_waitcnt lgkmcnt(0)
	v_add_f32_e32 v56, v56, v57
	v_mov_b32_e32 v57, v56
	s_nop 1
	v_permlane32_swap_b32 v56, v57
	s_and_saveexec_b64 s[4:5], vcc
	s_cbranch_execz .LBB0_585
	v_lshl_add_u64 v[162:163], v[72:73], 2, s[14:15]
	s_waitcnt lgkmcnt(0)
	v_add_f32_e32 v56, v56, v57
	global_atomic_add_f32 v[162:163], v56, off
;     __device__ __forceinline__ void operator()(f32x4 (&acc)[2][2][4][2], const pg8::Unit& u, int wr, int wc, int fr, int fq) const {
;     ...
;         for (int ai = 0; ai < 2; ++ai)
; #pragma unroll
;             for (int m = 0; m < 4; ++m) {
;                 const int row = row0 + ai * 128 + m * 16;
;                 float ss = 0.f;
; #pragma unroll
;                 for (int bj = 0; bj < 2; ++bj) {
;                     const int c = col0 + bj * 128;
;                     const h16x8 r8 = *(const h16x8*)(res16 + (size_t)row * D + c);
;                     f32x4 v0 = acc[ai][bj][m][0], v1 = acc[ai][bj][m][1];
; #pragma unroll
;                     for (int j = 0; j < 4; ++j) { v0[j] += (float)r8[j]; v1[j] += (float)r8[4 + j]; }
;                     acc[ai][bj][m][0] = v0; acc[ai][bj][m][1] = v1;
;                     ss += v0[0] * v0[0] + v0[1] * v0[1] + v0[2] * v0[2] + v0[3] * v0[3] + v1[0] * v1[0] + v1[1] * v1[1] + v1[2] * v1[2] + v1[3] * v1[3];
;                 }
;                 ss += __shfl_xor(ss, 16); ss += __shfl_xor(ss, 32);
;                 if (fq == 0) atomicAdd(rowss + row, ss);
.LBB0_585:
	s_or_b64 exec, exec, s[4:5]
	v_add_u32_e32 v56, 0x90, v138
	s_waitcnt lgkmcnt(0)
	v_ashrrev_i32_e32 v57, 31, v56
	v_lshlrev_b64 v[162:163], 11, v[56:57]
	v_lshl_add_u64 v[162:163], s[10:11], 0, v[162:163]
	v_lshl_add_u64 v[168:169], v[140:141], 1, v[162:163]
	v_mov_b32_e32 v162, v228
	v_mov_b32_e32 v163, v229
	v_mov_b32_e32 v164, v230
	v_mov_b32_e32 v165, v231
	s_nop 0
	v_mov_b32_e32 v168, v232
	v_mov_b32_e32 v169, v233
	v_mov_b32_e32 v170, v234
	v_mov_b32_e32 v171, v235
	s_nop 0
	v_cvt_f32_f16_e32 v172, v162
	v_cvt_f32_f16_sdwa v173, v162 dst_sel:DWORD dst_unused:UNUSED_PAD src0_sel:WORD_1
	s_nop 0
	v_cvt_f32_f16_e32 v178, v168
	v_cvt_f32_f16_sdwa v179, v168 dst_sel:DWORD dst_unused:UNUSED_PAD src0_sel:WORD_1
	v_cvt_f32_f16_e32 v174, v164
	v_cvt_f32_f16_sdwa v175, v164 dst_sel:DWORD dst_unused:UNUSED_PAD src0_sel:WORD_1
	v_cvt_f32_f16_e32 v176, v163
	v_cvt_f32_f16_sdwa v177, v163 dst_sel:DWORD dst_unused:UNUSED_PAD src0_sel:WORD_1
	v_cvt_f32_f16_e32 v168, v169
	v_cvt_f32_f16_sdwa v169, v169 dst_sel:DWORD dst_unused:UNUSED_PAD src0_sel:WORD_1
	v_cvt_f32_f16_e32 v164, v165
	v_cvt_f32_f16_sdwa v165, v165 dst_sel:DWORD dst_unused:UNUSED_PAD src0_sel:WORD_1
	v_cvt_f32_f16_e32 v180, v170
	v_cvt_f32_f16_sdwa v181, v170 dst_sel:DWORD dst_unused:UNUSED_PAD src0_sel:WORD_1
	v_pk_add_f32 v[162:163], v[44:45], v[172:173]
	v_pk_add_f32 v[36:37], v[36:37], v[178:179]
	v_cvt_f32_f16_e32 v170, v171
	v_cvt_f32_f16_sdwa v171, v171 dst_sel:DWORD dst_unused:UNUSED_PAD src0_sel:WORD_1
	v_pk_add_f32 v[44:45], v[40:41], v[174:175]
	v_pk_add_f32 v[46:47], v[46:47], v[176:177]
	v_pk_add_f32 v[38:39], v[38:39], v[168:169]
	v_pk_mul_f32 v[40:41], v[162:163], v[162:163]
	v_pk_mul_f32 v[172:173], v[36:37], v[36:37]
	v_pk_add_f32 v[42:43], v[42:43], v[164:165]
	v_pk_mul_f32 v[164:165], v[46:47], v[46:47]
	v_pk_mul_f32 v[174:175], v[38:39], v[38:39]
	v_add_f32_e32 v137, v172, v173
	v_add_f32_e32 v40, v40, v41
	v_pk_add_f32 v[32:33], v[32:33], v[180:181]
	v_add_f32_e32 v41, v174, v137
	v_add_f32_e32 v40, v164, v40
	v_pk_mul_f32 v[168:169], v[44:45], v[44:45]
	v_pk_mul_f32 v[176:177], v[32:33], v[32:33]
	v_add_f32_e32 v41, v175, v41
	v_add_f32_e32 v40, v165, v40
	v_pk_add_f32 v[34:35], v[34:35], v[170:171]
	v_add_f32_e32 v41, v176, v41
	v_add_f32_e32 v40, v168, v40
	v_pk_mul_f32 v[170:171], v[42:43], v[42:43]
	v_pk_mul_f32 v[178:179], v[34:35], v[34:35]
	v_add_f32_e32 v41, v177, v41
	v_add_f32_e32 v40, v169, v40
	v_add_f32_e32 v41, v178, v41
	v_add_f32_e32 v40, v170, v40
	v_add_f32_e32 v41, v179, v41
	v_add_f32_e32 v40, v171, v40
	v_add_f32_e32 v40, v40, v41
	v_mov_b32_e32 v41, v40
	s_nop 1
	v_permlane16_swap_b32 v40, v41
	s_waitcnt lgkmcnt(0)
	v_add_f32_e32 v40, v40, v41
	v_mov_b32_e32 v41, v40
	s_nop 1
	v_permlane32_swap_b32 v40, v41
	s_and_saveexec_b64 s[4:5], vcc
	s_cbranch_execz .LBB0_587
	v_lshl_add_u64 v[164:165], v[56:57], 2, s[14:15]
	s_waitcnt lgkmcnt(0)
	v_add_f32_e32 v40, v40, v41
	global_atomic_add_f32 v[164:165], v40, off
;     __device__ __forceinline__ void operator()(f32x4 (&acc)[2][2][4][2], const pg8::Unit& u, int wr, int wc, int fr, int fq) const {
;     ...
;         for (int ai = 0; ai < 2; ++ai)
; #pragma unroll
;             for (int m = 0; m < 4; ++m) {
;                 const int row = row0 + ai * 128 + m * 16;
;                 float ss = 0.f;
; #pragma unroll
;                 for (int bj = 0; bj < 2; ++bj) {
;                     const int c = col0 + bj * 128;
;                     const h16x8 r8 = *(const h16x8*)(res16 + (size_t)row * D + c);
;                     f32x4 v0 = acc[ai][bj][m][0], v1 = acc[ai][bj][m][1];
; #pragma unroll
;                     for (int j = 0; j < 4; ++j) { v0[j] += (float)r8[j]; v1[j] += (float)r8[4 + j]; }
;                     acc[ai][bj][m][0] = v0; acc[ai][bj][m][1] = v1;
;                     ss += v0[0] * v0[0] + v0[1] * v0[1] + v0[2] * v0[2] + v0[3] * v0[3] + v1[0] * v1[0] + v1[1] * v1[1] + v1[2] * v1[2] + v1[3] * v1[3];
;                 }
;                 ss += __shfl_xor(ss, 16); ss += __shfl_xor(ss, 32);
;                 if (fq == 0) atomicAdd(rowss + row, ss);
.LBB0_587:
	s_or_b64 exec, exec, s[4:5]
	v_add_u32_e32 v40, 0xa0, v138
	s_waitcnt lgkmcnt(0)
	v_ashrrev_i32_e32 v41, 31, v40
	v_lshlrev_b64 v[164:165], 11, v[40:41]
	v_lshl_add_u64 v[164:165], s[10:11], 0, v[164:165]
	v_lshl_add_u64 v[164:165], v[140:141], 1, v[164:165]
	v_mov_b32_e32 v168, v236
	v_mov_b32_e32 v169, v237
	v_mov_b32_e32 v170, v238
	v_mov_b32_e32 v171, v239
	v_mov_b32_e32 v172, v240
	v_mov_b32_e32 v173, v241
	v_mov_b32_e32 v174, v242
	v_mov_b32_e32 v175, v243
	s_nop 0
	v_cvt_f32_f16_e32 v164, v168
	v_cvt_f32_f16_sdwa v165, v168 dst_sel:DWORD dst_unused:UNUSED_PAD src0_sel:WORD_1
	s_nop 0
	v_cvt_f32_f16_e32 v178, v172
	v_cvt_f32_f16_sdwa v179, v172 dst_sel:DWORD dst_unused:UNUSED_PAD src0_sel:WORD_1
	v_cvt_f32_f16_e32 v176, v170
	v_cvt_f32_f16_sdwa v177, v170 dst_sel:DWORD dst_unused:UNUSED_PAD src0_sel:WORD_1
	v_cvt_f32_f16_e32 v168, v169
	v_cvt_f32_f16_sdwa v169, v169 dst_sel:DWORD dst_unused:UNUSED_PAD src0_sel:WORD_1
	v_cvt_f32_f16_e32 v180, v174
	v_cvt_f32_f16_sdwa v181, v174 dst_sel:DWORD dst_unused:UNUSED_PAD src0_sel:WORD_1
	v_cvt_f32_f16_e32 v172, v173
	v_cvt_f32_f16_sdwa v173, v173 dst_sel:DWORD dst_unused:UNUSED_PAD src0_sel:WORD_1
	v_cvt_f32_f16_e32 v174, v175
	v_cvt_f32_f16_sdwa v175, v175 dst_sel:DWORD dst_unused:UNUSED_PAD src0_sel:WORD_1
	v_cvt_f32_f16_e32 v170, v171
	v_cvt_f32_f16_sdwa v171, v171 dst_sel:DWORD dst_unused:UNUSED_PAD src0_sel:WORD_1
	v_pk_add_f32 v[164:165], v[28:29], v[164:165]
	v_pk_add_f32 v[20:21], v[20:21], v[178:179]
	v_pk_add_f32 v[28:29], v[24:25], v[176:177]
	v_pk_add_f32 v[30:31], v[30:31], v[168:169]
	v_pk_add_f32 v[22:23], v[22:23], v[172:173]
	v_pk_add_f32 v[18:19], v[18:19], v[174:175]
	v_pk_mul_f32 v[24:25], v[164:165], v[164:165]
	v_pk_mul_f32 v[174:175], v[20:21], v[20:21]
	v_pk_mul_f32 v[168:169], v[30:31], v[30:31]
	v_pk_mul_f32 v[176:177], v[22:23], v[22:23]
	v_add_f32_e32 v137, v174, v175
	v_add_f32_e32 v24, v24, v25
	v_pk_add_f32 v[16:17], v[16:17], v[180:181]
	v_add_f32_e32 v25, v176, v137
	v_add_f32_e32 v24, v168, v24
	v_pk_add_f32 v[26:27], v[26:27], v[170:171]
	v_pk_mul_f32 v[170:171], v[28:29], v[28:29]
	v_pk_mul_f32 v[178:179], v[16:17], v[16:17]
	v_add_f32_e32 v25, v177, v25
	v_add_f32_e32 v24, v169, v24
	v_add_f32_e32 v25, v178, v25
	v_add_f32_e32 v24, v170, v24
	v_pk_mul_f32 v[172:173], v[26:27], v[26:27]
	v_pk_mul_f32 v[180:181], v[18:19], v[18:19]
	v_add_f32_e32 v25, v179, v25
	v_add_f32_e32 v24, v171, v24
	v_add_f32_e32 v25, v180, v25
	v_add_f32_e32 v24, v172, v24
	v_add_f32_e32 v25, v181, v25
	v_add_f32_e32 v24, v173, v24
	v_add_f32_e32 v24, v24, v25
	v_mov_b32_e32 v25, v24
	s_nop 1
	v_permlane16_swap_b32 v24, v25
	s_waitcnt lgkmcnt(0)
	v_add_f32_e32 v24, v24, v25
	v_mov_b32_e32 v25, v24
	s_nop 1
	v_permlane32_swap_b32 v24, v25
	s_and_saveexec_b64 s[4:5], vcc
	s_cbranch_execz .LBB0_589
	v_lshl_add_u64 v[168:169], v[40:41], 2, s[14:15]
	s_waitcnt lgkmcnt(0)
	v_add_f32_e32 v24, v24, v25
	global_atomic_add_f32 v[168:169], v24, off
.LBB0_589:
	s_or_b64 exec, exec, s[4:5]
	v_add_u32_e32 v24, 0xb0, v138
	s_waitcnt lgkmcnt(0)
	v_ashrrev_i32_e32 v25, 31, v24
	v_lshlrev_b64 v[168:169], 11, v[24:25]
	v_lshl_add_u64 v[168:169], s[10:11], 0, v[168:169]
	v_lshl_add_u64 v[172:173], v[140:141], 1, v[168:169]
	v_mov_b32_e32 v168, v244
	v_mov_b32_e32 v169, v245
	v_mov_b32_e32 v170, v246
	v_mov_b32_e32 v171, v247
	s_nop 0
	v_mov_b32_e32 v172, v248
	v_mov_b32_e32 v173, v249
	v_mov_b32_e32 v174, v250
	v_mov_b32_e32 v175, v251
	s_nop 0
	v_cvt_f32_f16_e32 v176, v168
	v_cvt_f32_f16_sdwa v177, v168 dst_sel:DWORD dst_unused:UNUSED_PAD src0_sel:WORD_1
	s_nop 0
	v_cvt_f32_f16_e32 v180, v172
	v_cvt_f32_f16_sdwa v181, v172 dst_sel:DWORD dst_unused:UNUSED_PAD src0_sel:WORD_1
	v_cvt_f32_f16_e32 v168, v169
	v_cvt_f32_f16_sdwa v169, v169 dst_sel:DWORD dst_unused:UNUSED_PAD src0_sel:WORD_1
	v_cvt_f32_f16_e32 v172, v173
	v_cvt_f32_f16_sdwa v173, v173 dst_sel:DWORD dst_unused:UNUSED_PAD src0_sel:WORD_1
	v_cvt_f32_f16_e32 v178, v170
	v_cvt_f32_f16_sdwa v179, v170 dst_sel:DWORD dst_unused:UNUSED_PAD src0_sel:WORD_1
	v_cvt_f32_f16_e32 v170, v171
	v_cvt_f32_f16_sdwa v171, v171 dst_sel:DWORD dst_unused:UNUSED_PAD src0_sel:WORD_1
	v_cvt_f32_f16_e32 v182, v174
	v_cvt_f32_f16_sdwa v183, v174 dst_sel:DWORD dst_unused:UNUSED_PAD src0_sel:WORD_1
	v_pk_add_f32 v[12:13], v[12:13], v[176:177]
	v_pk_add_f32 v[4:5], v[4:5], v[180:181]
	v_cvt_f32_f16_e32 v174, v175
	v_cvt_f32_f16_sdwa v175, v175 dst_sel:DWORD dst_unused:UNUSED_PAD src0_sel:WORD_1
	v_pk_add_f32 v[14:15], v[14:15], v[168:169]
	v_pk_add_f32 v[6:7], v[6:7], v[172:173]
	v_pk_mul_f32 v[168:169], v[12:13], v[12:13]
	v_pk_mul_f32 v[176:177], v[4:5], v[4:5]
	v_pk_add_f32 v[8:9], v[8:9], v[178:179]
	v_pk_add_f32 v[10:11], v[10:11], v[170:171]
	v_pk_mul_f32 v[170:171], v[14:15], v[14:15]
	v_pk_mul_f32 v[178:179], v[6:7], v[6:7]
	v_add_f32_e32 v137, v176, v177
	v_add_f32_e32 v167, v168, v169
	v_pk_add_f32 v[0:1], v[0:1], v[182:183]
	v_add_f32_e32 v137, v178, v137
	v_add_f32_e32 v167, v170, v167
	v_pk_mul_f32 v[172:173], v[8:9], v[8:9]
	v_pk_mul_f32 v[180:181], v[0:1], v[0:1]
	v_add_f32_e32 v137, v179, v137
	v_add_f32_e32 v167, v171, v167
	v_pk_add_f32 v[2:3], v[2:3], v[174:175]
	v_add_f32_e32 v137, v180, v137
	v_add_f32_e32 v167, v172, v167
	v_pk_mul_f32 v[174:175], v[10:11], v[10:11]
	v_pk_mul_f32 v[182:183], v[2:3], v[2:3]
	v_add_f32_e32 v137, v181, v137
	v_add_f32_e32 v167, v173, v167
	v_add_f32_e32 v137, v182, v137
	v_add_f32_e32 v167, v174, v167
	v_add_f32_e32 v137, v183, v137
	v_add_f32_e32 v167, v175, v167
	v_add_f32_e32 v137, v167, v137
	v_mov_b32_e32 v147, v137
	s_nop 1
	v_permlane16_swap_b32 v137, v147
	s_waitcnt lgkmcnt(0)
	v_add_f32_e32 v137, v137, v147
	v_mov_b32_e32 v147, v137
	s_nop 1
	v_permlane32_swap_b32 v137, v147
	s_and_saveexec_b64 s[4:5], vcc
	s_cbranch_execz .LBB0_591
	v_lshl_add_u64 v[166:167], v[24:25], 2, s[14:15]
	s_waitcnt lgkmcnt(0)
	v_add_f32_e32 v137, v137, v147
	global_atomic_add_f32 v[166:167], v137, off

;     __device__ __forceinline__ void operator()(f32x4 (&acc)[2][2][4][2], const pg8::Unit& u, int wr, int wc, int fr, int fq) const {
;     ...
; #pragma unroll
;         for (int ai = 0; ai < 2; ++ai)
; #pragma unroll
;             for (int m = 0; m < 4; ++m) {
;                 const int row = row0 + ai * 128 + m * 16;
;                 const float rstd = rsqrtf(__hip_atomic_load(rowss + row, __ATOMIC_RELAXED, __HIP_MEMORY_SCOPE_AGENT) * (1.f / 1024.f) + EPS);
; #pragma unroll
;                 for (int bj = 0; bj < 2; ++bj) {
;                     const int c = col0 + bj * 128;
;                     const f32x4 w0 = *(const f32x4*)(nw + c), w1 = *(const f32x4*)(nw + c + 4);
;                     float* op = out + (size_t)row * D + c;
;                     *(f32x4*)op = acc[ai][bj][m][0] * rstd * w0; *(f32x4*)(op + 4) = acc[ai][bj][m][1] * rstd * w1;
;                 }
.LBB0_605:
	s_or_b64 exec, exec, s[4:5]
	s_barrier
	v_cmp_gt_u32_e64 s[98:99], 8, v131
	v_mov_b32_e32 v240, 0xffff8010
	v_cndmask_b32_e64 v236, v240, 0, s[98:99]
	v_cndmask_b32_e64 v237, -1, 0, s[98:99]
	v_mov_b32_e32 v240, 0x8010
	v_cndmask_b32_e64 v238, 0, v240, s[98:99]
	v_mov_b32_e32 v239, 0
	global_load_dword v147, v[112:113], off sc1
	global_load_dword v185, v[112:113], off offset:64 sc1
	global_load_dword v186, v[112:113], off offset:128 sc1
	global_load_dword v187, v[112:113], off offset:192 sc1
	global_load_dword v188, v[112:113], off offset:512 sc1
	global_load_dword v189, v[112:113], off offset:576 sc1
	global_load_dword v190, v[112:113], off offset:640 sc1
	global_load_dword v191, v[112:113], off offset:704 sc1
	v_lshlrev_b64 v[166:167], 2, v[140:141]
	v_lshl_add_u64 v[140:141], s[60:61], 0, v[166:167]
	global_load_dwordx4 v[168:171], v[140:141], off
	global_load_dwordx4 v[172:175], v[140:141], off offset:16
	global_load_dwordx4 v[204:207], v[140:141], off offset:512
	global_load_dwordx4 v[208:211], v[140:141], off offset:528
	v_mov_b32_e32 v137, 0x358637bd
	s_mov_b32 s0, 0x800000
	v_lshlrev_b64 v[138:139], 12, v[138:139]
	v_lshl_add_u64 v[138:139], s[62:63], 0, v[138:139]
	v_lshl_add_u64 v[138:139], v[138:139], 0, v[166:167]
	v_lshlrev_b64 v[104:105], 12, v[104:105]
	v_lshl_add_u64 v[104:105], s[62:63], 0, v[104:105]
	v_lshl_add_u64 v[104:105], v[104:105], 0, v[166:167]
	v_lshlrev_b64 v[88:89], 12, v[88:89]
	v_lshl_add_u64 v[88:89], s[62:63], 0, v[88:89]
	v_lshl_add_u64 v[88:89], v[88:89], 0, v[166:167]
	v_lshlrev_b64 v[72:73], 12, v[72:73]
	v_lshl_add_u64 v[72:73], s[62:63], 0, v[72:73]
	v_lshl_add_u64 v[72:73], v[72:73], 0, v[166:167]
	v_lshlrev_b64 v[56:57], 12, v[56:57]
	v_lshl_add_u64 v[56:57], s[62:63], 0, v[56:57]
	v_lshl_add_u64 v[56:57], v[56:57], 0, v[166:167]
	v_lshlrev_b64 v[40:41], 12, v[40:41]
	v_lshl_add_u64 v[40:41], s[62:63], 0, v[40:41]
	v_lshl_add_u64 v[40:41], v[40:41], 0, v[166:167]
	v_lshlrev_b64 v[24:25], 12, v[24:25]
	v_lshl_add_u64 v[24:25], s[62:63], 0, v[24:25]
	v_lshl_add_u64 v[24:25], v[24:25], 0, v[166:167]
	s_waitcnt vmcnt(0)
	v_mov_b32_e32 v192, v168
	v_mov_b32_e32 v193, v169
	v_mov_b32_e32 v194, v170
	v_mov_b32_e32 v195, v171
	v_mov_b32_e32 v196, v172
	v_mov_b32_e32 v197, v173
	v_mov_b32_e32 v198, v174
	v_mov_b32_e32 v199, v175
	v_fmamk_f32 v147, v147, 0x3a800000, v137
	v_mul_f32_e32 v176, 0x4b800000, v147
	v_cmp_gt_f32_e32 vcc, s0, v147
	s_nop 1
	v_cndmask_b32_e32 v147, v147, v176, vcc
	v_rsq_f32_e32 v147, v147
	s_nop 0
	v_mul_f32_e32 v176, 0x45800000, v147
	v_cndmask_b32_e32 v176, v147, v176, vcc
	v_pk_mul_f32 v[142:143], v[142:143], v[176:177] op_sel_hi:[1,0]
	v_pk_mul_f32 v[126:127], v[126:127], v[176:177] op_sel_hi:[1,0]
	v_pk_mul_f32 v[178:179], v[124:125], v[176:177] op_sel_hi:[1,0]
	v_pk_mul_f32 v[180:181], v[122:123], v[176:177] op_sel_hi:[1,0]
	s_nop 0
	v_pk_mul_f32 v[124:125], v[170:171], v[126:127]
	v_pk_mul_f32 v[122:123], v[168:169], v[142:143]
	s_nop 0
	v_pk_mul_f32 v[170:171], v[174:175], v[180:181]
	v_pk_mul_f32 v[168:169], v[172:173], v[178:179]
	s_nop 1
	v_mov_b32_dpp v228, v168 row_ror:8 row_mask:0xf bank_mask:0xf
	v_mov_b32_dpp v229, v169 row_ror:8 row_mask:0xf bank_mask:0xf
	v_mov_b32_dpp v230, v170 row_ror:8 row_mask:0xf bank_mask:0xf
	v_mov_b32_dpp v231, v171 row_ror:8 row_mask:0xf bank_mask:0xf
	v_cndmask_b32_e64 v168, v228, v122, s[98:99]
	v_cndmask_b32_e64 v169, v229, v123, s[98:99]
	v_cndmask_b32_e64 v170, v230, v124, s[98:99]
	v_cndmask_b32_e64 v171, v231, v125, s[98:99]
	v_cndmask_b32_e64 v228, v122, v228, s[98:99]
	v_cndmask_b32_e64 v229, v123, v229, s[98:99]
	v_cndmask_b32_e64 v230, v124, v230, s[98:99]
	v_cndmask_b32_e64 v231, v125, v231, s[98:99]
	v_lshl_add_u64 v[232:233], v[138:139], 0, v[236:237]
	v_lshl_add_u64 v[234:235], v[138:139], 0, v[238:239]
	global_store_dwordx4 v[232:233], v[168:171], off sc0 sc1
	global_store_dwordx4 v[234:235], v[228:231], off sc0 sc1
	s_nop 1
	v_mov_b32_e32 v122, v204
	v_mov_b32_e32 v123, v205
	v_mov_b32_e32 v124, v206
	v_mov_b32_e32 v125, v207
	s_nop 0
	s_nop 1
	v_mov_b32_e32 v168, v208
	v_mov_b32_e32 v169, v209
	v_mov_b32_e32 v170, v210
	v_mov_b32_e32 v171, v211
	v_pk_mul_f32 v[118:119], v[118:119], v[176:177] op_sel_hi:[1,0]
	v_pk_mul_f32 v[120:121], v[120:121], v[176:177] op_sel_hi:[1,0]
	v_pk_mul_f32 v[126:127], v[114:115], v[176:177] op_sel_hi:[1,0]
	v_pk_mul_f32 v[142:143], v[116:117], v[176:177] op_sel_hi:[1,0]
	s_nop 0
	v_pk_mul_f32 v[114:115], v[122:123], v[120:121]
	v_pk_mul_f32 v[116:117], v[124:125], v[118:119]
	s_nop 0
	v_pk_mul_f32 v[118:119], v[168:169], v[142:143]
	v_pk_mul_f32 v[120:121], v[170:171], v[126:127]
	s_nop 1
	v_mov_b32_dpp v228, v118 row_ror:8 row_mask:0xf bank_mask:0xf
	v_mov_b32_dpp v229, v119 row_ror:8 row_mask:0xf bank_mask:0xf
	v_mov_b32_dpp v230, v120 row_ror:8 row_mask:0xf bank_mask:0xf
	v_mov_b32_dpp v231, v121 row_ror:8 row_mask:0xf bank_mask:0xf
	v_cndmask_b32_e64 v118, v228, v114, s[98:99]
	v_cndmask_b32_e64 v119, v229, v115, s[98:99]
	v_cndmask_b32_e64 v120, v230, v116, s[98:99]
	v_cndmask_b32_e64 v121, v231, v117, s[98:99]
	v_cndmask_b32_e64 v228, v114, v228, s[98:99]
	v_cndmask_b32_e64 v229, v115, v229, s[98:99]
	v_cndmask_b32_e64 v230, v116, v230, s[98:99]
	v_cndmask_b32_e64 v231, v117, v231, s[98:99]
	v_lshl_add_u64 v[232:233], v[138:139], 0, v[236:237]
	v_lshl_add_u64 v[234:235], v[138:139], 0, v[238:239]
	global_store_dwordx4 v[232:233], v[118:121], off offset:512 sc0 sc1
	global_store_dwordx4 v[234:235], v[228:231], off offset:512 sc0 sc1
	s_nop 1
	v_mov_b32_e32 v122, v185
	s_nop 0
	s_nop 1
	v_mov_b32_e32 v114, v192
	v_mov_b32_e32 v115, v193
	v_mov_b32_e32 v116, v194
;     __device__ __forceinline__ void operator()(f32x4 (&acc)[2][2][4][2], const pg8::Unit& u, int wr, int wc, int fr, int fq) const {
;     ...
;         for (int ai = 0; ai < 2; ++ai)
; #pragma unroll
;             for (int m = 0; m < 4; ++m) {
;                 const int row = row0 + ai * 128 + m * 16;
;                 const float rstd = rsqrtf(__hip_atomic_load(rowss + row, __ATOMIC_RELAXED, __HIP_MEMORY_SCOPE_AGENT) * (1.f / 1024.f) + EPS);
; #pragma unroll
;                 for (int bj = 0; bj < 2; ++bj) {
;                     const int c = col0 + bj * 128;
;                     const f32x4 w0 = *(const f32x4*)(nw + c), w1 = *(const f32x4*)(nw + c + 4);
;                     float* op = out + (size_t)row * D + c;
;                     *(f32x4*)op = acc[ai][bj][m][0] * rstd * w0; *(f32x4*)(op + 4) = acc[ai][bj][m][1] * rstd * w1;
;                 }
	v_mov_b32_e32 v117, v195
	s_nop 1
	v_mov_b32_e32 v118, v196
	v_mov_b32_e32 v119, v197
	v_mov_b32_e32 v120, v198
	v_mov_b32_e32 v121, v199
	s_nop 0
	v_fmamk_f32 v122, v122, 0x3a800000, v137
	v_mul_f32_e32 v123, 0x4b800000, v122
	v_cmp_gt_f32_e32 vcc, s0, v122
	s_nop 1
	v_cndmask_b32_e32 v122, v122, v123, vcc
	v_rsq_f32_e32 v124, v122
	v_lshlrev_b64 v[122:123], 12, v[144:145]
	v_lshl_add_u64 v[122:123], s[62:63], 0, v[122:123]
	v_lshl_add_u64 v[122:123], v[122:123], 0, v[166:167]
	v_mul_f32_e32 v125, 0x45800000, v124
	v_cndmask_b32_e32 v124, v124, v125, vcc
	v_pk_mul_f32 v[126:127], v[148:149], v[124:125] op_sel_hi:[1,0]
	v_pk_mul_f32 v[110:111], v[110:111], v[124:125] op_sel_hi:[1,0]
	v_pk_mul_f32 v[138:139], v[108:109], v[124:125] op_sel_hi:[1,0]
	v_pk_mul_f32 v[142:143], v[106:107], v[124:125] op_sel_hi:[1,0]
	s_nop 0
	v_pk_mul_f32 v[108:109], v[116:117], v[110:111]
	v_pk_mul_f32 v[106:107], v[114:115], v[126:127]
	s_nop 0
	v_pk_mul_f32 v[116:117], v[120:121], v[142:143]
	v_pk_mul_f32 v[114:115], v[118:119], v[138:139]
	s_nop 1
	v_mov_b32_dpp v228, v114 row_ror:8 row_mask:0xf bank_mask:0xf
	v_mov_b32_dpp v229, v115 row_ror:8 row_mask:0xf bank_mask:0xf
	v_mov_b32_dpp v230, v116 row_ror:8 row_mask:0xf bank_mask:0xf
	v_mov_b32_dpp v231, v117 row_ror:8 row_mask:0xf bank_mask:0xf
	v_cndmask_b32_e64 v114, v228, v106, s[98:99]
	v_cndmask_b32_e64 v115, v229, v107, s[98:99]
	v_cndmask_b32_e64 v116, v230, v108, s[98:99]
	v_cndmask_b32_e64 v117, v231, v109, s[98:99]
	v_cndmask_b32_e64 v228, v106, v228, s[98:99]
	v_cndmask_b32_e64 v229, v107, v229, s[98:99]
	v_cndmask_b32_e64 v230, v108, v230, s[98:99]
	v_cndmask_b32_e64 v231, v109, v231, s[98:99]
	v_lshl_add_u64 v[232:233], v[122:123], 0, v[236:237]
	v_lshl_add_u64 v[234:235], v[122:123], 0, v[238:239]
	global_store_dwordx4 v[232:233], v[114:117], off sc0 sc1
	global_store_dwordx4 v[234:235], v[228:231], off sc0 sc1
	s_nop 1
	v_mov_b32_e32 v106, v204
	v_mov_b32_e32 v107, v205
	v_mov_b32_e32 v108, v206
	v_mov_b32_e32 v109, v207
	s_nop 0
	s_nop 1
	v_mov_b32_e32 v114, v208
	v_mov_b32_e32 v115, v209
	v_mov_b32_e32 v116, v210
	v_mov_b32_e32 v117, v211
	v_pk_mul_f32 v[102:103], v[102:103], v[124:125] op_sel_hi:[1,0]
	v_pk_mul_f32 v[100:101], v[100:101], v[124:125] op_sel_hi:[1,0]
	v_pk_mul_f32 v[110:111], v[98:99], v[124:125] op_sel_hi:[1,0]
	v_pk_mul_f32 v[118:119], v[96:97], v[124:125] op_sel_hi:[1,0]
	s_nop 0
	v_pk_mul_f32 v[96:97], v[106:107], v[100:101]
	v_pk_mul_f32 v[98:99], v[108:109], v[102:103]
	s_nop 0
	v_pk_mul_f32 v[100:101], v[114:115], v[118:119]
	v_pk_mul_f32 v[102:103], v[116:117], v[110:111]
	s_nop 1
	v_mov_b32_dpp v228, v100 row_ror:8 row_mask:0xf bank_mask:0xf
	v_mov_b32_dpp v229, v101 row_ror:8 row_mask:0xf bank_mask:0xf
	v_mov_b32_dpp v230, v102 row_ror:8 row_mask:0xf bank_mask:0xf
	v_mov_b32_dpp v231, v103 row_ror:8 row_mask:0xf bank_mask:0xf
	v_cndmask_b32_e64 v100, v228, v96, s[98:99]
	v_cndmask_b32_e64 v101, v229, v97, s[98:99]
	v_cndmask_b32_e64 v102, v230, v98, s[98:99]
	v_cndmask_b32_e64 v103, v231, v99, s[98:99]
	v_cndmask_b32_e64 v228, v96, v228, s[98:99]
	v_cndmask_b32_e64 v229, v97, v229, s[98:99]
	v_cndmask_b32_e64 v230, v98, v230, s[98:99]
	v_cndmask_b32_e64 v231, v99, v231, s[98:99]
	v_lshl_add_u64 v[232:233], v[122:123], 0, v[236:237]
	v_lshl_add_u64 v[234:235], v[122:123], 0, v[238:239]
	global_store_dwordx4 v[232:233], v[100:103], off offset:512 sc0 sc1
	global_store_dwordx4 v[234:235], v[228:231], off offset:512 sc0 sc1
	s_nop 1
	v_mov_b32_e32 v106, v186
	s_nop 0
	s_nop 1
	v_mov_b32_e32 v96, v192
	v_mov_b32_e32 v97, v193
	v_mov_b32_e32 v98, v194
	v_mov_b32_e32 v99, v195
	s_nop 1
	v_mov_b32_e32 v100, v196
	v_mov_b32_e32 v101, v197
	v_mov_b32_e32 v102, v198
	v_mov_b32_e32 v103, v199
	s_nop 0
	v_fmamk_f32 v106, v106, 0x3a800000, v137
	v_mul_f32_e32 v107, 0x4b800000, v106
	v_cmp_gt_f32_e32 vcc, s0, v106
	s_nop 1
	v_cndmask_b32_e32 v106, v106, v107, vcc
	v_rsq_f32_e32 v106, v106
	s_nop 0
	v_mul_f32_e32 v107, 0x45800000, v106
	v_cndmask_b32_e32 v106, v106, v107, vcc
	v_pk_mul_f32 v[108:109], v[150:151], v[106:107] op_sel_hi:[1,0]
	v_pk_mul_f32 v[94:95], v[94:95], v[106:107] op_sel_hi:[1,0]
	v_pk_mul_f32 v[110:111], v[92:93], v[106:107] op_sel_hi:[1,0]
	v_pk_mul_f32 v[114:115], v[90:91], v[106:107] op_sel_hi:[1,0]
	s_nop 0
	v_pk_mul_f32 v[92:93], v[98:99], v[94:95]
	v_pk_mul_f32 v[90:91], v[96:97], v[108:109]
	s_nop 0
	v_pk_mul_f32 v[96:97], v[102:103], v[114:115]
	v_pk_mul_f32 v[94:95], v[100:101], v[110:111]
	s_nop 1
	v_mov_b32_dpp v228, v94 row_ror:8 row_mask:0xf bank_mask:0xf
	v_mov_b32_dpp v229, v95 row_ror:8 row_mask:0xf bank_mask:0xf
	v_mov_b32_dpp v230, v96 row_ror:8 row_mask:0xf bank_mask:0xf
	v_mov_b32_dpp v231, v97 row_ror:8 row_mask:0xf bank_mask:0xf
	v_cndmask_b32_e64 v94, v228, v90, s[98:99]
	v_cndmask_b32_e64 v95, v229, v91, s[98:99]
	v_cndmask_b32_e64 v96, v230, v92, s[98:99]
	v_cndmask_b32_e64 v97, v231, v93, s[98:99]
	v_cndmask_b32_e64 v228, v90, v228, s[98:99]
	v_cndmask_b32_e64 v229, v91, v229, s[98:99]
	v_cndmask_b32_e64 v230, v92, v230, s[98:99]
	v_cndmask_b32_e64 v231, v93, v231, s[98:99]
	v_lshl_add_u64 v[232:233], v[104:105], 0, v[236:237]
	v_lshl_add_u64 v[234:235], v[104:105], 0, v[238:239]
	global_store_dwordx4 v[232:233], v[94:97], off sc0 sc1
	global_store_dwordx4 v[234:235], v[228:231], off sc0 sc1
	s_nop 1
	v_mov_b32_e32 v90, v204
	v_mov_b32_e32 v91, v205
	v_mov_b32_e32 v92, v206
	v_mov_b32_e32 v93, v207
	s_nop 0
	s_nop 1
	v_mov_b32_e32 v94, v208
	v_mov_b32_e32 v95, v209
	v_mov_b32_e32 v96, v210
	v_mov_b32_e32 v97, v211
	v_pk_mul_f32 v[86:87], v[86:87], v[106:107] op_sel_hi:[1,0]
	v_pk_mul_f32 v[84:85], v[84:85], v[106:107] op_sel_hi:[1,0]
;     __device__ __forceinline__ void operator()(f32x4 (&acc)[2][2][4][2], const pg8::Unit& u, int wr, int wc, int fr, int fq) const {
;     ...
;         for (int ai = 0; ai < 2; ++ai)
; #pragma unroll
;             for (int m = 0; m < 4; ++m) {
;                 const int row = row0 + ai * 128 + m * 16;
;                 const float rstd = rsqrtf(__hip_atomic_load(rowss + row, __ATOMIC_RELAXED, __HIP_MEMORY_SCOPE_AGENT) * (1.f / 1024.f) + EPS);
; #pragma unroll
;                 for (int bj = 0; bj < 2; ++bj) {
;                     const int c = col0 + bj * 128;
;                     const f32x4 w0 = *(const f32x4*)(nw + c), w1 = *(const f32x4*)(nw + c + 4);
;                     float* op = out + (size_t)row * D + c;
;                     *(f32x4*)op = acc[ai][bj][m][0] * rstd * w0; *(f32x4*)(op + 4) = acc[ai][bj][m][1] * rstd * w1;
;                 }
	v_pk_mul_f32 v[98:99], v[82:83], v[106:107] op_sel_hi:[1,0]
	v_pk_mul_f32 v[100:101], v[80:81], v[106:107] op_sel_hi:[1,0]
	s_nop 0
	v_pk_mul_f32 v[80:81], v[90:91], v[84:85]
	v_pk_mul_f32 v[82:83], v[92:93], v[86:87]
	s_nop 0
	v_pk_mul_f32 v[84:85], v[94:95], v[100:101]
	v_pk_mul_f32 v[86:87], v[96:97], v[98:99]
	s_nop 1
	v_mov_b32_dpp v228, v84 row_ror:8 row_mask:0xf bank_mask:0xf
	v_mov_b32_dpp v229, v85 row_ror:8 row_mask:0xf bank_mask:0xf
	v_mov_b32_dpp v230, v86 row_ror:8 row_mask:0xf bank_mask:0xf
	v_mov_b32_dpp v231, v87 row_ror:8 row_mask:0xf bank_mask:0xf
	v_cndmask_b32_e64 v84, v228, v80, s[98:99]
	v_cndmask_b32_e64 v85, v229, v81, s[98:99]
	v_cndmask_b32_e64 v86, v230, v82, s[98:99]
	v_cndmask_b32_e64 v87, v231, v83, s[98:99]
	v_cndmask_b32_e64 v228, v80, v228, s[98:99]
	v_cndmask_b32_e64 v229, v81, v229, s[98:99]
	v_cndmask_b32_e64 v230, v82, v230, s[98:99]
	v_cndmask_b32_e64 v231, v83, v231, s[98:99]
	v_lshl_add_u64 v[232:233], v[104:105], 0, v[236:237]
	v_lshl_add_u64 v[234:235], v[104:105], 0, v[238:239]
	global_store_dwordx4 v[232:233], v[84:87], off offset:512 sc0 sc1
	global_store_dwordx4 v[234:235], v[228:231], off offset:512 sc0 sc1
	s_nop 1
	v_mov_b32_e32 v90, v187
	s_nop 0
	s_nop 1
	v_mov_b32_e32 v80, v192
	v_mov_b32_e32 v81, v193
	v_mov_b32_e32 v82, v194
	v_mov_b32_e32 v83, v195
	s_nop 1
	v_mov_b32_e32 v84, v196
	v_mov_b32_e32 v85, v197
	v_mov_b32_e32 v86, v198
	v_mov_b32_e32 v87, v199
	s_nop 0
	v_fmamk_f32 v90, v90, 0x3a800000, v137
	v_mul_f32_e32 v91, 0x4b800000, v90
	v_cmp_gt_f32_e32 vcc, s0, v90
	s_nop 1
	v_cndmask_b32_e32 v90, v90, v91, vcc
	v_rsq_f32_e32 v90, v90
	s_nop 0
	v_mul_f32_e32 v91, 0x45800000, v90
	v_cndmask_b32_e32 v90, v90, v91, vcc
	v_pk_mul_f32 v[92:93], v[154:155], v[90:91] op_sel_hi:[1,0]
	v_pk_mul_f32 v[78:79], v[78:79], v[90:91] op_sel_hi:[1,0]
	v_pk_mul_f32 v[94:95], v[76:77], v[90:91] op_sel_hi:[1,0]
	v_pk_mul_f32 v[96:97], v[74:75], v[90:91] op_sel_hi:[1,0]
	s_nop 0
	v_pk_mul_f32 v[76:77], v[82:83], v[78:79]
	v_pk_mul_f32 v[74:75], v[80:81], v[92:93]
	s_nop 0
	v_pk_mul_f32 v[80:81], v[86:87], v[96:97]
	v_pk_mul_f32 v[78:79], v[84:85], v[94:95]
	s_nop 1
	v_mov_b32_dpp v228, v78 row_ror:8 row_mask:0xf bank_mask:0xf
	v_mov_b32_dpp v229, v79 row_ror:8 row_mask:0xf bank_mask:0xf
	v_mov_b32_dpp v230, v80 row_ror:8 row_mask:0xf bank_mask:0xf
	v_mov_b32_dpp v231, v81 row_ror:8 row_mask:0xf bank_mask:0xf
	v_cndmask_b32_e64 v78, v228, v74, s[98:99]
	v_cndmask_b32_e64 v79, v229, v75, s[98:99]
	v_cndmask_b32_e64 v80, v230, v76, s[98:99]
	v_cndmask_b32_e64 v81, v231, v77, s[98:99]
	v_cndmask_b32_e64 v228, v74, v228, s[98:99]
	v_cndmask_b32_e64 v229, v75, v229, s[98:99]
	v_cndmask_b32_e64 v230, v76, v230, s[98:99]
	v_cndmask_b32_e64 v231, v77, v231, s[98:99]
	v_lshl_add_u64 v[232:233], v[88:89], 0, v[236:237]
	v_lshl_add_u64 v[234:235], v[88:89], 0, v[238:239]
	global_store_dwordx4 v[232:233], v[78:81], off sc0 sc1
	global_store_dwordx4 v[234:235], v[228:231], off sc0 sc1
	s_nop 1
	v_mov_b32_e32 v74, v204
	v_mov_b32_e32 v75, v205
	v_mov_b32_e32 v76, v206
	v_mov_b32_e32 v77, v207
	s_nop 0
	s_nop 1
	v_mov_b32_e32 v78, v208
	v_mov_b32_e32 v79, v209
	v_mov_b32_e32 v80, v210
	v_mov_b32_e32 v81, v211
	v_pk_mul_f32 v[70:71], v[70:71], v[90:91] op_sel_hi:[1,0]
	v_pk_mul_f32 v[68:69], v[68:69], v[90:91] op_sel_hi:[1,0]
	v_pk_mul_f32 v[82:83], v[66:67], v[90:91] op_sel_hi:[1,0]
	v_pk_mul_f32 v[84:85], v[64:65], v[90:91] op_sel_hi:[1,0]
	s_nop 0
	v_pk_mul_f32 v[64:65], v[74:75], v[68:69]
	v_pk_mul_f32 v[66:67], v[76:77], v[70:71]
	s_nop 0
	v_pk_mul_f32 v[68:69], v[78:79], v[84:85]
	v_pk_mul_f32 v[70:71], v[80:81], v[82:83]
	s_nop 1
	v_mov_b32_dpp v228, v68 row_ror:8 row_mask:0xf bank_mask:0xf
	v_mov_b32_dpp v229, v69 row_ror:8 row_mask:0xf bank_mask:0xf
	v_mov_b32_dpp v230, v70 row_ror:8 row_mask:0xf bank_mask:0xf
	v_mov_b32_dpp v231, v71 row_ror:8 row_mask:0xf bank_mask:0xf
	v_cndmask_b32_e64 v68, v228, v64, s[98:99]
	v_cndmask_b32_e64 v69, v229, v65, s[98:99]
	v_cndmask_b32_e64 v70, v230, v66, s[98:99]
	v_cndmask_b32_e64 v71, v231, v67, s[98:99]
	v_cndmask_b32_e64 v228, v64, v228, s[98:99]
	v_cndmask_b32_e64 v229, v65, v229, s[98:99]
	v_cndmask_b32_e64 v230, v66, v230, s[98:99]
	v_cndmask_b32_e64 v231, v67, v231, s[98:99]
	v_lshl_add_u64 v[232:233], v[88:89], 0, v[236:237]
	v_lshl_add_u64 v[234:235], v[88:89], 0, v[238:239]
	global_store_dwordx4 v[232:233], v[68:71], off offset:512 sc0 sc1
	global_store_dwordx4 v[234:235], v[228:231], off offset:512 sc0 sc1
	s_nop 1
	v_mov_b32_e32 v74, v188
	s_nop 0
	s_nop 1
	v_mov_b32_e32 v64, v192
	v_mov_b32_e32 v65, v193
	v_mov_b32_e32 v66, v194
	v_mov_b32_e32 v67, v195
	s_nop 1
	v_mov_b32_e32 v68, v196
	v_mov_b32_e32 v69, v197
	v_mov_b32_e32 v70, v198
	v_mov_b32_e32 v71, v199
	s_nop 0
	v_fmamk_f32 v74, v74, 0x3a800000, v137
	v_mul_f32_e32 v75, 0x4b800000, v74
	v_cmp_gt_f32_e32 vcc, s0, v74
	s_nop 1
	v_cndmask_b32_e32 v74, v74, v75, vcc
	v_rsq_f32_e32 v74, v74
	s_nop 0
	v_mul_f32_e32 v75, 0x45800000, v74
	v_cndmask_b32_e32 v74, v74, v75, vcc
	v_pk_mul_f32 v[76:77], v[158:159], v[74:75] op_sel_hi:[1,0]
	v_pk_mul_f32 v[62:63], v[62:63], v[74:75] op_sel_hi:[1,0]
	v_pk_mul_f32 v[78:79], v[60:61], v[74:75] op_sel_hi:[1,0]
	v_pk_mul_f32 v[80:81], v[58:59], v[74:75] op_sel_hi:[1,0]
	s_nop 0
	v_pk_mul_f32 v[60:61], v[66:67], v[62:63]
	v_pk_mul_f32 v[58:59], v[64:65], v[76:77]
	s_nop 0
	v_pk_mul_f32 v[64:65], v[70:71], v[80:81]
	v_pk_mul_f32 v[62:63], v[68:69], v[78:79]
	s_nop 1
	v_mov_b32_dpp v228, v62 row_ror:8 row_mask:0xf bank_mask:0xf
	v_mov_b32_dpp v229, v63 row_ror:8 row_mask:0xf bank_mask:0xf
	v_mov_b32_dpp v230, v64 row_ror:8 row_mask:0xf bank_mask:0xf
;     __device__ __forceinline__ void operator()(f32x4 (&acc)[2][2][4][2], const pg8::Unit& u, int wr, int wc, int fr, int fq) const {
;     ...
;         for (int ai = 0; ai < 2; ++ai)
; #pragma unroll
;             for (int m = 0; m < 4; ++m) {
;                 const int row = row0 + ai * 128 + m * 16;
;                 const float rstd = rsqrtf(__hip_atomic_load(rowss + row, __ATOMIC_RELAXED, __HIP_MEMORY_SCOPE_AGENT) * (1.f / 1024.f) + EPS);
; #pragma unroll
;                 for (int bj = 0; bj < 2; ++bj) {
;                     const int c = col0 + bj * 128;
;                     const f32x4 w0 = *(const f32x4*)(nw + c), w1 = *(const f32x4*)(nw + c + 4);
;                     float* op = out + (size_t)row * D + c;
;                     *(f32x4*)op = acc[ai][bj][m][0] * rstd * w0; *(f32x4*)(op + 4) = acc[ai][bj][m][1] * rstd * w1;
;                 }
;             }
	v_mov_b32_dpp v231, v65 row_ror:8 row_mask:0xf bank_mask:0xf
	v_cndmask_b32_e64 v62, v228, v58, s[98:99]
	v_cndmask_b32_e64 v63, v229, v59, s[98:99]
	v_cndmask_b32_e64 v64, v230, v60, s[98:99]
	v_cndmask_b32_e64 v65, v231, v61, s[98:99]
	v_cndmask_b32_e64 v228, v58, v228, s[98:99]
	v_cndmask_b32_e64 v229, v59, v229, s[98:99]
	v_cndmask_b32_e64 v230, v60, v230, s[98:99]
	v_cndmask_b32_e64 v231, v61, v231, s[98:99]
	v_lshl_add_u64 v[232:233], v[72:73], 0, v[236:237]
	v_lshl_add_u64 v[234:235], v[72:73], 0, v[238:239]
	global_store_dwordx4 v[232:233], v[62:65], off sc0 sc1
	global_store_dwordx4 v[234:235], v[228:231], off sc0 sc1
	s_nop 1
	v_mov_b32_e32 v58, v204
	v_mov_b32_e32 v59, v205
	v_mov_b32_e32 v60, v206
	v_mov_b32_e32 v61, v207
	s_nop 0
	s_nop 1
	v_mov_b32_e32 v62, v208
	v_mov_b32_e32 v63, v209
	v_mov_b32_e32 v64, v210
	v_mov_b32_e32 v65, v211
	v_pk_mul_f32 v[54:55], v[54:55], v[74:75] op_sel_hi:[1,0]
	v_pk_mul_f32 v[52:53], v[52:53], v[74:75] op_sel_hi:[1,0]
	v_pk_mul_f32 v[66:67], v[50:51], v[74:75] op_sel_hi:[1,0]
	v_pk_mul_f32 v[68:69], v[48:49], v[74:75] op_sel_hi:[1,0]
	s_nop 0
	v_pk_mul_f32 v[48:49], v[58:59], v[52:53]
	v_pk_mul_f32 v[50:51], v[60:61], v[54:55]
	s_nop 0
	v_pk_mul_f32 v[52:53], v[62:63], v[68:69]
	v_pk_mul_f32 v[54:55], v[64:65], v[66:67]
	s_nop 1
	v_mov_b32_dpp v228, v52 row_ror:8 row_mask:0xf bank_mask:0xf
	v_mov_b32_dpp v229, v53 row_ror:8 row_mask:0xf bank_mask:0xf
	v_mov_b32_dpp v230, v54 row_ror:8 row_mask:0xf bank_mask:0xf
	v_mov_b32_dpp v231, v55 row_ror:8 row_mask:0xf bank_mask:0xf
	v_cndmask_b32_e64 v52, v228, v48, s[98:99]
	v_cndmask_b32_e64 v53, v229, v49, s[98:99]
	v_cndmask_b32_e64 v54, v230, v50, s[98:99]
	v_cndmask_b32_e64 v55, v231, v51, s[98:99]
	v_cndmask_b32_e64 v228, v48, v228, s[98:99]
	v_cndmask_b32_e64 v229, v49, v229, s[98:99]
	v_cndmask_b32_e64 v230, v50, v230, s[98:99]
	v_cndmask_b32_e64 v231, v51, v231, s[98:99]
	v_lshl_add_u64 v[232:233], v[72:73], 0, v[236:237]
	v_lshl_add_u64 v[234:235], v[72:73], 0, v[238:239]
	global_store_dwordx4 v[232:233], v[52:55], off offset:512 sc0 sc1
	global_store_dwordx4 v[234:235], v[228:231], off offset:512 sc0 sc1
	s_nop 1
	v_mov_b32_e32 v58, v189
	s_nop 0
	s_nop 1
	v_mov_b32_e32 v48, v192
	v_mov_b32_e32 v49, v193
	v_mov_b32_e32 v50, v194
	v_mov_b32_e32 v51, v195
	s_nop 1
	v_mov_b32_e32 v52, v196
	v_mov_b32_e32 v53, v197
	v_mov_b32_e32 v54, v198
	v_mov_b32_e32 v55, v199
	s_nop 0
	v_fmamk_f32 v58, v58, 0x3a800000, v137
	v_mul_f32_e32 v59, 0x4b800000, v58
	v_cmp_gt_f32_e32 vcc, s0, v58
	s_nop 1
	v_cndmask_b32_e32 v58, v58, v59, vcc
	v_rsq_f32_e32 v58, v58
	s_nop 0
	v_mul_f32_e32 v59, 0x45800000, v58
	v_cndmask_b32_e32 v58, v58, v59, vcc
	v_pk_mul_f32 v[60:61], v[162:163], v[58:59] op_sel_hi:[1,0]
	v_pk_mul_f32 v[46:47], v[46:47], v[58:59] op_sel_hi:[1,0]
	v_pk_mul_f32 v[62:63], v[44:45], v[58:59] op_sel_hi:[1,0]
	v_pk_mul_f32 v[64:65], v[42:43], v[58:59] op_sel_hi:[1,0]
	s_nop 0
	v_pk_mul_f32 v[44:45], v[50:51], v[46:47]
	v_pk_mul_f32 v[42:43], v[48:49], v[60:61]
	s_nop 0
	v_pk_mul_f32 v[48:49], v[54:55], v[64:65]
	v_pk_mul_f32 v[46:47], v[52:53], v[62:63]
	s_nop 1
	v_mov_b32_dpp v228, v46 row_ror:8 row_mask:0xf bank_mask:0xf
	v_mov_b32_dpp v229, v47 row_ror:8 row_mask:0xf bank_mask:0xf
	v_mov_b32_dpp v230, v48 row_ror:8 row_mask:0xf bank_mask:0xf
	v_mov_b32_dpp v231, v49 row_ror:8 row_mask:0xf bank_mask:0xf
	v_cndmask_b32_e64 v46, v228, v42, s[98:99]
	v_cndmask_b32_e64 v47, v229, v43, s[98:99]
	v_cndmask_b32_e64 v48, v230, v44, s[98:99]
	v_cndmask_b32_e64 v49, v231, v45, s[98:99]
	v_cndmask_b32_e64 v228, v42, v228, s[98:99]
	v_cndmask_b32_e64 v229, v43, v229, s[98:99]
	v_cndmask_b32_e64 v230, v44, v230, s[98:99]
	v_cndmask_b32_e64 v231, v45, v231, s[98:99]
	v_lshl_add_u64 v[232:233], v[56:57], 0, v[236:237]
	v_lshl_add_u64 v[234:235], v[56:57], 0, v[238:239]
	global_store_dwordx4 v[232:233], v[46:49], off sc0 sc1
	global_store_dwordx4 v[234:235], v[228:231], off sc0 sc1
	s_nop 1
	v_mov_b32_e32 v42, v204
	v_mov_b32_e32 v43, v205
	v_mov_b32_e32 v44, v206
	v_mov_b32_e32 v45, v207
	s_nop 0
	s_nop 1
	v_mov_b32_e32 v46, v208
	v_mov_b32_e32 v47, v209
	v_mov_b32_e32 v48, v210
	v_mov_b32_e32 v49, v211
	v_pk_mul_f32 v[38:39], v[38:39], v[58:59] op_sel_hi:[1,0]
	v_pk_mul_f32 v[36:37], v[36:37], v[58:59] op_sel_hi:[1,0]
	v_pk_mul_f32 v[50:51], v[34:35], v[58:59] op_sel_hi:[1,0]
	v_pk_mul_f32 v[52:53], v[32:33], v[58:59] op_sel_hi:[1,0]
	s_nop 0
	v_pk_mul_f32 v[32:33], v[42:43], v[36:37]
	v_pk_mul_f32 v[34:35], v[44:45], v[38:39]
	s_nop 0
	v_pk_mul_f32 v[36:37], v[46:47], v[52:53]
	v_pk_mul_f32 v[38:39], v[48:49], v[50:51]
	s_nop 1
	v_mov_b32_dpp v228, v36 row_ror:8 row_mask:0xf bank_mask:0xf
	v_mov_b32_dpp v229, v37 row_ror:8 row_mask:0xf bank_mask:0xf
	v_mov_b32_dpp v230, v38 row_ror:8 row_mask:0xf bank_mask:0xf
	v_mov_b32_dpp v231, v39 row_ror:8 row_mask:0xf bank_mask:0xf
	v_cndmask_b32_e64 v36, v228, v32, s[98:99]
	v_cndmask_b32_e64 v37, v229, v33, s[98:99]
	v_cndmask_b32_e64 v38, v230, v34, s[98:99]
	v_cndmask_b32_e64 v39, v231, v35, s[98:99]
	v_cndmask_b32_e64 v228, v32, v228, s[98:99]
	v_cndmask_b32_e64 v229, v33, v229, s[98:99]
	v_cndmask_b32_e64 v230, v34, v230, s[98:99]
	v_cndmask_b32_e64 v231, v35, v231, s[98:99]
	v_lshl_add_u64 v[232:233], v[56:57], 0, v[236:237]
	v_lshl_add_u64 v[234:235], v[56:57], 0, v[238:239]
	global_store_dwordx4 v[232:233], v[36:39], off offset:512 sc0 sc1
	global_store_dwordx4 v[234:235], v[228:231], off offset:512 sc0 sc1
	s_nop 1
	v_mov_b32_e32 v42, v190
	s_nop 0
	s_nop 1
	v_mov_b32_e32 v32, v192
	v_mov_b32_e32 v33, v193
	v_mov_b32_e32 v34, v194
	v_mov_b32_e32 v35, v195
	s_nop 1
	v_mov_b32_e32 v36, v196
	v_mov_b32_e32 v37, v197
;     __device__ __forceinline__ void operator()(f32x4 (&acc)[2][2][4][2], const pg8::Unit& u, int wr, int wc, int fr, int fq) const {
;     ...
;         for (int ai = 0; ai < 2; ++ai)
; #pragma unroll
;             for (int m = 0; m < 4; ++m) {
;                 const int row = row0 + ai * 128 + m * 16;
;                 const float rstd = rsqrtf(__hip_atomic_load(rowss + row, __ATOMIC_RELAXED, __HIP_MEMORY_SCOPE_AGENT) * (1.f / 1024.f) + EPS);
; #pragma unroll
;                 for (int bj = 0; bj < 2; ++bj) {
;                     const int c = col0 + bj * 128;
;                     const f32x4 w0 = *(const f32x4*)(nw + c), w1 = *(const f32x4*)(nw + c + 4);
;                     float* op = out + (size_t)row * D + c;
;                     *(f32x4*)op = acc[ai][bj][m][0] * rstd * w0; *(f32x4*)(op + 4) = acc[ai][bj][m][1] * rstd * w1;
;                 }
;             }
	v_mov_b32_e32 v38, v198
	v_mov_b32_e32 v39, v199
	s_nop 0
	v_fmamk_f32 v42, v42, 0x3a800000, v137
	v_mul_f32_e32 v43, 0x4b800000, v42
	v_cmp_gt_f32_e32 vcc, s0, v42
	s_nop 1
	v_cndmask_b32_e32 v42, v42, v43, vcc
	v_rsq_f32_e32 v42, v42
	s_nop 0
	v_mul_f32_e32 v43, 0x45800000, v42
	v_cndmask_b32_e32 v42, v42, v43, vcc
	v_pk_mul_f32 v[44:45], v[164:165], v[42:43] op_sel_hi:[1,0]
	v_pk_mul_f32 v[30:31], v[30:31], v[42:43] op_sel_hi:[1,0]
	v_pk_mul_f32 v[46:47], v[28:29], v[42:43] op_sel_hi:[1,0]
	v_pk_mul_f32 v[48:49], v[26:27], v[42:43] op_sel_hi:[1,0]
	s_nop 0
	v_pk_mul_f32 v[28:29], v[34:35], v[30:31]
	v_pk_mul_f32 v[26:27], v[32:33], v[44:45]
	s_nop 0
	v_pk_mul_f32 v[32:33], v[38:39], v[48:49]
	v_pk_mul_f32 v[30:31], v[36:37], v[46:47]
	s_nop 1
	v_mov_b32_dpp v228, v30 row_ror:8 row_mask:0xf bank_mask:0xf
	v_mov_b32_dpp v229, v31 row_ror:8 row_mask:0xf bank_mask:0xf
	v_mov_b32_dpp v230, v32 row_ror:8 row_mask:0xf bank_mask:0xf
	v_mov_b32_dpp v231, v33 row_ror:8 row_mask:0xf bank_mask:0xf
	v_cndmask_b32_e64 v30, v228, v26, s[98:99]
	v_cndmask_b32_e64 v31, v229, v27, s[98:99]
	v_cndmask_b32_e64 v32, v230, v28, s[98:99]
	v_cndmask_b32_e64 v33, v231, v29, s[98:99]
	v_cndmask_b32_e64 v228, v26, v228, s[98:99]
	v_cndmask_b32_e64 v229, v27, v229, s[98:99]
	v_cndmask_b32_e64 v230, v28, v230, s[98:99]
	v_cndmask_b32_e64 v231, v29, v231, s[98:99]
	v_lshl_add_u64 v[232:233], v[40:41], 0, v[236:237]
	v_lshl_add_u64 v[234:235], v[40:41], 0, v[238:239]
	global_store_dwordx4 v[232:233], v[30:33], off sc0 sc1
	global_store_dwordx4 v[234:235], v[228:231], off sc0 sc1
	s_nop 1
	v_mov_b32_e32 v26, v204
	v_mov_b32_e32 v27, v205
	v_mov_b32_e32 v28, v206
	v_mov_b32_e32 v29, v207
	s_nop 0
	s_nop 1
	v_mov_b32_e32 v30, v208
	v_mov_b32_e32 v31, v209
	v_mov_b32_e32 v32, v210
	v_mov_b32_e32 v33, v211
	v_pk_mul_f32 v[22:23], v[22:23], v[42:43] op_sel_hi:[1,0]
	v_pk_mul_f32 v[20:21], v[20:21], v[42:43] op_sel_hi:[1,0]
	v_pk_mul_f32 v[34:35], v[18:19], v[42:43] op_sel_hi:[1,0]
	v_pk_mul_f32 v[36:37], v[16:17], v[42:43] op_sel_hi:[1,0]
	s_nop 0
	v_pk_mul_f32 v[16:17], v[26:27], v[20:21]
	v_pk_mul_f32 v[18:19], v[28:29], v[22:23]
	s_nop 0
	v_pk_mul_f32 v[20:21], v[30:31], v[36:37]
	v_pk_mul_f32 v[22:23], v[32:33], v[34:35]
	s_nop 1
	v_mov_b32_dpp v228, v20 row_ror:8 row_mask:0xf bank_mask:0xf
	v_mov_b32_dpp v229, v21 row_ror:8 row_mask:0xf bank_mask:0xf
	v_mov_b32_dpp v230, v22 row_ror:8 row_mask:0xf bank_mask:0xf
	v_mov_b32_dpp v231, v23 row_ror:8 row_mask:0xf bank_mask:0xf
	v_cndmask_b32_e64 v20, v228, v16, s[98:99]
	v_cndmask_b32_e64 v21, v229, v17, s[98:99]
	v_cndmask_b32_e64 v22, v230, v18, s[98:99]
	v_cndmask_b32_e64 v23, v231, v19, s[98:99]
	v_cndmask_b32_e64 v228, v16, v228, s[98:99]
	v_cndmask_b32_e64 v229, v17, v229, s[98:99]
	v_cndmask_b32_e64 v230, v18, v230, s[98:99]
	v_cndmask_b32_e64 v231, v19, v231, s[98:99]
	v_lshl_add_u64 v[232:233], v[40:41], 0, v[236:237]
	v_lshl_add_u64 v[234:235], v[40:41], 0, v[238:239]
	global_store_dwordx4 v[232:233], v[20:23], off offset:512 sc0 sc1
	global_store_dwordx4 v[234:235], v[228:231], off offset:512 sc0 sc1
	s_nop 1
	v_mov_b32_e32 v26, v191
	s_nop 0
	s_nop 1
	v_mov_b32_e32 v16, v192
	v_mov_b32_e32 v17, v193
	v_mov_b32_e32 v18, v194
	v_mov_b32_e32 v19, v195
	s_nop 1
	v_mov_b32_e32 v20, v196
	v_mov_b32_e32 v21, v197
	v_mov_b32_e32 v22, v198
	v_mov_b32_e32 v23, v199
	s_nop 0
	v_fmac_f32_e32 v137, 0x3a800000, v26
	v_mul_f32_e32 v26, 0x4b800000, v137
	v_cmp_gt_f32_e32 vcc, s0, v137
	s_nop 1
	v_cndmask_b32_e32 v26, v137, v26, vcc
	v_rsq_f32_e32 v26, v26
	s_nop 0
	v_mul_f32_e32 v27, 0x45800000, v26
	v_cndmask_b32_e32 v26, v26, v27, vcc
	v_pk_mul_f32 v[12:13], v[12:13], v[26:27] op_sel_hi:[1,0]
	v_pk_mul_f32 v[14:15], v[14:15], v[26:27] op_sel_hi:[1,0]
	v_pk_mul_f32 v[28:29], v[8:9], v[26:27] op_sel_hi:[1,0]
	v_pk_mul_f32 v[30:31], v[10:11], v[26:27] op_sel_hi:[1,0]
	s_nop 0
	v_pk_mul_f32 v[10:11], v[18:19], v[14:15]
	v_pk_mul_f32 v[8:9], v[16:17], v[12:13]
	s_nop 0
	v_pk_mul_f32 v[14:15], v[22:23], v[30:31]
	v_pk_mul_f32 v[12:13], v[20:21], v[28:29]
	s_nop 1
	v_mov_b32_dpp v228, v12 row_ror:8 row_mask:0xf bank_mask:0xf
	v_mov_b32_dpp v229, v13 row_ror:8 row_mask:0xf bank_mask:0xf
	v_mov_b32_dpp v230, v14 row_ror:8 row_mask:0xf bank_mask:0xf
	v_mov_b32_dpp v231, v15 row_ror:8 row_mask:0xf bank_mask:0xf
	v_cndmask_b32_e64 v12, v228, v8, s[98:99]
	v_cndmask_b32_e64 v13, v229, v9, s[98:99]
	v_cndmask_b32_e64 v14, v230, v10, s[98:99]
	v_cndmask_b32_e64 v15, v231, v11, s[98:99]
	v_cndmask_b32_e64 v228, v8, v228, s[98:99]
	v_cndmask_b32_e64 v229, v9, v229, s[98:99]
	v_cndmask_b32_e64 v230, v10, v230, s[98:99]
	v_cndmask_b32_e64 v231, v11, v231, s[98:99]
	v_lshl_add_u64 v[232:233], v[24:25], 0, v[236:237]
	v_lshl_add_u64 v[234:235], v[24:25], 0, v[238:239]
	global_store_dwordx4 v[232:233], v[12:15], off sc0 sc1
	global_store_dwordx4 v[234:235], v[228:231], off sc0 sc1
	s_nop 1
	v_mov_b32_e32 v8, v204
	v_mov_b32_e32 v9, v205
	v_mov_b32_e32 v10, v206
	v_mov_b32_e32 v11, v207
	s_nop 0
	s_nop 1
	v_mov_b32_e32 v12, v208
	v_mov_b32_e32 v13, v209
	v_mov_b32_e32 v14, v210
	v_mov_b32_e32 v15, v211
	v_pk_mul_f32 v[6:7], v[6:7], v[26:27] op_sel_hi:[1,0]
	v_pk_mul_f32 v[4:5], v[4:5], v[26:27] op_sel_hi:[1,0]
	v_pk_mul_f32 v[16:17], v[2:3], v[26:27] op_sel_hi:[1,0]
	v_pk_mul_f32 v[18:19], v[0:1], v[26:27] op_sel_hi:[1,0]
	s_nop 0
	v_pk_mul_f32 v[0:1], v[8:9], v[4:5]
	v_pk_mul_f32 v[2:3], v[10:11], v[6:7]
	s_nop 0
	v_pk_mul_f32 v[4:5], v[12:13], v[18:19]
	v_pk_mul_f32 v[6:7], v[14:15], v[16:17]
	s_nop 1
	v_mov_b32_dpp v228, v4 row_ror:8 row_mask:0xf bank_mask:0xf
	v_mov_b32_dpp v229, v5 row_ror:8 row_mask:0xf bank_mask:0xf
	v_mov_b32_dpp v230, v6 row_ror:8 row_mask:0xf bank_mask:0xf
	v_mov_b32_dpp v231, v7 row_ror:8 row_mask:0xf bank_mask:0xf
	v_cndmask_b32_e64 v4, v228, v0, s[98:99]
	v_cndmask_b32_e64 v5, v229, v1, s[98:99]
	v_cndmask_b32_e64 v6, v230, v2, s[98:99]
	v_cndmask_b32_e64 v7, v231, v3, s[98:99]
	v_cndmask_b32_e64 v228, v0, v228, s[98:99]
	v_cndmask_b32_e64 v229, v1, v229, s[98:99]
	v_cndmask_b32_e64 v230, v2, v230, s[98:99]
	v_cndmask_b32_e64 v231, v3, v231, s[98:99]
	v_lshl_add_u64 v[232:233], v[24:25], 0, v[236:237]
	v_lshl_add_u64 v[234:235], v[24:25], 0, v[238:239]
	global_store_dwordx4 v[232:233], v[4:7], off offset:512 sc0 sc1
	global_store_dwordx4 v[234:235], v[228:231], off offset:512 sc0 sc1
